# P5 gated-merge epilogue rewritten (all gate/T loads in flight, counted waits); static s_setprio 1 for waves 0-3 in attention; nt policy on streamed h1/x/out
# speedup vs baseline: 1.0389x; 1.0131x over previous
; __device__ __forceinline__ void p0_prologue(const Params& p, LAS unsigned char* lds) {
;     ...
;           for (int q = 0; q < 2; ++q) { const int rq = r + q * NGW;
; #pragma unroll
;               for (int j = 0; j < 4; ++j) v[q][j] = (f32x4){0.f, 0.f, 0.f, 0.f};
;               if (rq < MR + NMETA) { const float* src = rq < MR ? p.x + (size_t)rq * DM : p.meta + (size_t)(rq - MR) * DM;
; #pragma unroll
;                   for (int j = 0; j < 4; ++j) v[q][j] = *(const f32x4*)(src + 4 * lane + 256 * j); } }
.LBB0_134:
	v_cmp_gt_i32_e32 vcc, s8, v50
	v_ashrrev_i32_e32 v51, 31, v50
	v_mov_b32_e32 v24, 0
	v_mov_b32_e32 v25, 0
	v_mov_b32_e32 v26, 0
	v_mov_b32_e32 v27, 0
	v_mov_b32_e32 v32, 0
	v_mov_b32_e32 v33, 0
	v_mov_b32_e32 v34, 0
	v_mov_b32_e32 v35, 0
	v_mov_b32_e32 v40, 0
	v_mov_b32_e32 v41, 0
	v_mov_b32_e32 v42, 0
	v_mov_b32_e32 v43, 0
	v_mov_b32_e32 v44, 0
	v_mov_b32_e32 v45, 0
	v_mov_b32_e32 v46, 0
	v_mov_b32_e32 v47, 0
	s_and_saveexec_b64 s[6:7], vcc
	s_cbranch_execz .LBB0_136
	v_add_u32_e32 v16, 0xffff0000, v50
	v_cmp_gt_i32_e32 vcc, s9, v50
	v_mov_b32_e32 v18, s39
	v_mov_b32_e32 v19, s37
	v_cndmask_b32_e32 v17, 0, v51, vcc
	v_cndmask_b32_e32 v16, v16, v50, vcc
	v_cndmask_b32_e32 v19, v18, v19, vcc
	v_mov_b32_e32 v18, s38
	v_mov_b32_e32 v20, s36
	v_cndmask_b32_e32 v18, v18, v20, vcc
	v_lshlrev_b64 v[16:17], 12, v[16:17]
	v_lshl_add_u64 v[16:17], v[18:19], 0, v[16:17]
	v_lshl_add_u64 v[16:17], v[16:17], 0, v[48:49]
	global_load_dwordx4 v[44:47], v[16:17], off nt
	global_load_dwordx4 v[40:43], v[16:17], off offset:1024 nt
	global_load_dwordx4 v[32:35], v[16:17], off offset:2048 nt
	global_load_dwordx4 v[24:27], v[16:17], off offset:3072 nt
.LBB0_136:
	s_or_b64 exec, exec, s[6:7]
	v_add_u32_e32 v54, s33, v50
	v_cmp_gt_i32_e32 vcc, s8, v54
	v_mov_b32_e32 v16, 0
	v_ashrrev_i32_e32 v55, 31, v54
	v_mov_b32_e32 v17, 0
	v_mov_b32_e32 v18, 0
	v_mov_b32_e32 v19, 0
	v_mov_b32_e32 v20, 0
	v_mov_b32_e32 v21, 0
	v_mov_b32_e32 v22, 0
	v_mov_b32_e32 v23, 0
	v_mov_b32_e32 v28, 0
	v_mov_b32_e32 v29, 0
	v_mov_b32_e32 v30, 0
	v_mov_b32_e32 v31, 0
	v_mov_b32_e32 v36, 0
	v_mov_b32_e32 v37, 0
	v_mov_b32_e32 v38, 0
	v_mov_b32_e32 v39, 0
	s_and_saveexec_b64 s[6:7], vcc
	s_cbranch_execz .LBB0_138
	v_add_u32_e32 v16, 0xffff0000, v54
	v_cmp_gt_i32_e32 vcc, s9, v54
	v_mov_b32_e32 v18, s39
	v_mov_b32_e32 v19, s37
	v_cndmask_b32_e32 v17, 0, v55, vcc
	v_cndmask_b32_e32 v16, v16, v54, vcc
	v_cndmask_b32_e32 v19, v18, v19, vcc
	v_mov_b32_e32 v18, s38
	v_mov_b32_e32 v20, s36
	v_cndmask_b32_e32 v18, v18, v20, vcc
	v_lshlrev_b64 v[16:17], 12, v[16:17]
	v_lshl_add_u64 v[16:17], v[18:19], 0, v[16:17]
	v_lshl_add_u64 v[64:65], v[16:17], 0, v[48:49]
	global_load_dwordx4 v[36:39], v[64:65], off nt
	global_load_dwordx4 v[28:31], v[64:65], off offset:1024 nt
	global_load_dwordx4 v[20:23], v[64:65], off offset:2048 nt
	global_load_dwordx4 v[16:19], v[64:65], off offset:3072 nt

; __device__ __forceinline__ void attn_phase(const Params& p, LAS unsigned char* lds) {
;     ...
;     int tid_ = threadIdx.x; asm volatile("" : "+v"(tid_));
;     const int tid = tid_, lane = tid & 63, wid = tid >> 6, c = lane & 31, hi = lane >> 5;
;     const float NEG = -__builtin_inff();
;     const int srow = tid >> 3, ssub = tid & 7;
;     const int G_ = gridDim.x, vcu = (G_ % 8 == 0) ? (int)(blockIdx.x & 7) * (G_ >> 3) + (int)(blockIdx.x >> 3) : (int)blockIdx.x;
;     for (int it = vcu; it < NBATCH * 8 * 4; it += G_) {
.LBB0_630:
	s_or_b64 exec, exec, s[0:1]
	v_readfirstlane_b32 s99, v201
	s_nop 3
	s_lshr_b32 s99, s99, 8
	s_cmp_eq_u32 s99, 0
	s_cbranch_scc0 .Lprio4_skip
	s_setprio 1
.Lprio4_skip:
	s_and_b32 s0, s30, 7
	s_waitcnt lgkmcnt(0)
	v_mov_b32_e32 v0, v201
	s_cmp_lg_u32 s0, 0
	s_mov_b32 s3, s2
	s_barrier
	s_cbranch_scc0 .LBB0_632
	s_cmpk_gt_i32 s3, 0x3ff
	s_cbranch_scc0 .LBB0_633
	s_branch .LBB0_652

; __device__ __forceinline__ unsigned xb_add(unsigned* p, unsigned v) { return __hip_atomic_fetch_add(p, v, __ATOMIC_RELAXED, __HIP_MEMORY_SCOPE_AGENT); }
; __device__ __forceinline__ void xcd_barrier(const XcdBarrier& b) {
;     asm volatile("s_waitcnt vmcnt(0)" ::: "memory");
;     __syncthreads();
;     if (threadIdx.x == 0) {
;         unsigned* bar = b.bar;
;         __builtin_amdgcn_s_waitcnt(0);
;         unsigned nloc = b.st[0], nx = b.st[1];
;         if (nloc == 0u) { xcd_barrier_complete(bar, b.x, nloc, nx); b.st[0] = nloc; b.st[1] = nx; }
;         const unsigned old = xb_add(&bar[XB_XSUB(b.x)], 1u);
.LBB0_652:
	s_waitcnt vmcnt(0)
	s_barrier
	s_setprio 0
	s_and_saveexec_b64 s[0:1], s[92:93]
	s_cbranch_execz .LBB0_704
	s_add_i32 s3, 0, 0x20400
	v_mov_b32_e32 v0, s3
	s_waitcnt vmcnt(0) expcnt(0) lgkmcnt(0)
	ds_read_b32 v2, v0
	s_add_i32 s3, 0, 0x20404
	v_mov_b32_e32 v0, s3
	ds_read_b32 v0, v0
	s_waitcnt lgkmcnt(1)
	v_cmp_ne_u32_e32 vcc, 0, v2
	s_cbranch_vccnz .LBB0_668
	s_add_u32 s4, s28, 0x180200
	s_addc_u32 s5, s29, 0
	s_add_u32 s6, s28, 0x180400
	s_addc_u32 s7, s29, 0
	s_add_u32 s8, s28, 0x180500
	s_addc_u32 s9, s29, 0
	s_add_u32 s10, s28, 0x180600
	s_addc_u32 s11, s29, 0
	s_add_u32 s12, s28, 0x180700
	s_addc_u32 s13, s29, 0
	s_add_u32 s14, s28, 0x180800
	s_addc_u32 s15, s29, 0
	s_add_u32 s42, s28, 0x180900
	s_addc_u32 s43, s29, 0
	s_add_u32 s44, s28, 0x180a00
	s_addc_u32 s45, s29, 0
	s_add_u32 s46, s28, 0x180b00
	s_addc_u32 s47, s29, 0
	s_add_u32 s48, s28, 0x180c00
	s_addc_u32 s49, s29, 0
	s_add_u32 s50, s28, 0x180d00
	s_addc_u32 s51, s29, 0
	s_add_u32 s52, s28, 0x180e00
	s_addc_u32 s53, s29, 0
	s_add_u32 s54, s28, 0x180f00
	s_addc_u32 s55, s29, 0
	s_add_u32 s56, s28, 0x181000
	s_addc_u32 s57, s29, 0
	s_add_u32 s58, s28, 0x181100
	s_addc_u32 s59, s29, 0
	s_add_u32 s60, s28, 0x181200
	v_readlane_b32 s3, v253, 0
	s_addc_u32 s61, s29, 0
	s_mul_i32 s3, s31, s3
	s_add_u32 s62, s28, 0x181300
	s_mul_i32 s3, s3, s30
	s_addc_u32 s63, s29, 0
	s_mov_b32 s74, 1
	v_mov_b32_e32 v16, 0
	s_branch .LBB0_656

; __device__ __forceinline__ u32x4 pack8(const f32x4 a, const f32x4 b) { u32x4 w; w.x = cvt_pk_bf16(a[0], a[1]); w.y = cvt_pk_bf16(a[2], a[3]); w.z = cvt_pk_bf16(b[0], b[1]); w.w = cvt_pk_bf16(b[2], b[3]); return w; }
; #define EPI_ROWLOOP _Pragma("unroll") for (int ai = 0; ai < 2; ++ai) _Pragma("unroll") for (int m = 0; m < 4; ++m)
;     __device__ __forceinline__ void operator()(const f32x4 (&acc)[2][2][4][2], const Unit& u, int wr, int wc, int fr, int fq) const {
;         const int row0 = u.pm * BM + wr * 64 + fr, c0 = u.pn * 256 + wc * 32 + 8 * fq;
;         EPI_ROWLOOP { const int r = row0 + ai * HALF + m * 16;
; #pragma unroll
;             for (int bj = 0; bj < 2; ++bj) { const int c = c0 + bj * HALF; f32x4 g0, g1; unpack8(*(const u32x4*)(GATES + (size_t)r * 2048 + (u.sel ? 1024 : 0) + c), g0, g1);
;                 f32x4 v0 = acc[ai][bj][m][0] * g0, v1 = acc[ai][bj][m][1] * g1;
;                 if (u.sel) { f32x4 t0, t1; unpack8(*(const u32x4*)(T + (size_t)r * 1024 + c), t0, t1); v0 += t0; v1 += t1; *(u32x4*)(MIX + (size_t)r * 1024 + c) = pack8(v0, v1); }
;                 else *(u32x4*)(T + (size_t)r * 1024 + c) = pack8(v0, v1); } }
;     }
.LBB0_731:
	v_lshl_add_u32 v162, s14, 8, v166
	v_lshl_or_b32 v163, s77, 8, v168
	s_cmp_eq_u32 s78, 0
	s_cselect_b32 s14, 0, 0x800
	v_lshlrev_b32_e32 v160, 12, v162
	v_lshl_add_u32 v160, v163, 1, v160
	v_add_u32_e32 v160, s14, v160
	v_mov_b32_e32 v161, 0
	v_lshlrev_b32_e32 v164, 11, v162
	v_lshl_add_u32 v164, v163, 1, v164
	v_mov_b32_e32 v165, 0
	v_lshl_add_u64 v[160:161], s[26:27], 0, v[160:161]
	s_mov_b64 s[6:7], 0x10000
	s_mov_b64 s[52:53], 0x50000
	global_load_dwordx4 v[172:175], v[160:161], off
	global_load_dwordx4 v[176:179], v[160:161], off offset:256
	v_lshl_add_u64 v[160:161], v[160:161], 0, s[6:7]
	global_load_dwordx4 v[180:183], v[160:161], off
	global_load_dwordx4 v[184:187], v[160:161], off offset:256
	v_lshl_add_u64 v[160:161], v[160:161], 0, s[6:7]
	global_load_dwordx4 v[188:191], v[160:161], off
	global_load_dwordx4 v[192:195], v[160:161], off offset:256
	v_lshl_add_u64 v[160:161], v[160:161], 0, s[6:7]
	global_load_dwordx4 v[196:199], v[160:161], off
	global_load_dwordx4 v[202:205], v[160:161], off offset:256
	v_lshl_add_u64 v[160:161], v[160:161], 0, s[52:53]
	global_load_dwordx4 v[206:209], v[160:161], off
	global_load_dwordx4 v[210:213], v[160:161], off offset:256
	v_lshl_add_u64 v[160:161], v[160:161], 0, s[6:7]
	global_load_dwordx4 v[214:217], v[160:161], off
	global_load_dwordx4 v[218:221], v[160:161], off offset:256
	v_lshl_add_u64 v[160:161], v[160:161], 0, s[6:7]
	global_load_dwordx4 v[222:225], v[160:161], off
	global_load_dwordx4 v[226:229], v[160:161], off offset:256
	v_lshl_add_u64 v[160:161], v[160:161], 0, s[6:7]
	global_load_dwordx4 v[230:233], v[160:161], off
	global_load_dwordx4 v[236:239], v[160:161], off offset:256
	s_cmp_eq_u32 s78, 0
	s_cbranch_scc1 .Lp5_sel0
	v_lshl_add_u64 v[160:161], s[34:35], 0, v[164:165]
	v_lshl_add_u64 v[164:165], s[24:25], 0, v[164:165]
	s_mov_b64 s[6:7], 0x8000
	s_mov_b64 s[52:53], 0x28000
	global_load_dwordx4 v[240:243], v[160:161], off
	global_load_dwordx4 v[244:247], v[160:161], off offset:256
	v_lshl_add_u64 v[160:161], v[160:161], 0, s[6:7]
	global_load_dwordx4 v[248:251], v[160:161], off
	global_load_dwordx4 v[128:131], v[160:161], off offset:256
	v_lshl_add_u64 v[160:161], v[160:161], 0, s[6:7]
	global_load_dwordx4 v[148:151], v[160:161], off
	s_waitcnt vmcnt(4)
	v_lshlrev_b32_e32 v152, 16, v172
	v_and_b32_e32 v153, 0xffff0000, v172
	v_pk_mul_f32 v[120:121], v[120:121], v[152:153]
	v_lshlrev_b32_e32 v154, 16, v173
	v_and_b32_e32 v155, 0xffff0000, v173
	v_pk_mul_f32 v[122:123], v[122:123], v[154:155]
	v_lshlrev_b32_e32 v156, 16, v174
	v_and_b32_e32 v157, 0xffff0000, v174
	v_pk_mul_f32 v[124:125], v[124:125], v[156:157]
	v_lshlrev_b32_e32 v158, 16, v175
	v_and_b32_e32 v159, 0xffff0000, v175
	v_pk_mul_f32 v[126:127], v[126:127], v[158:159]
	v_lshlrev_b32_e32 v152, 16, v240
	v_and_b32_e32 v153, 0xffff0000, v240
	v_pk_add_f32 v[120:121], v[120:121], v[152:153]
	v_lshlrev_b32_e32 v154, 16, v241
	v_and_b32_e32 v155, 0xffff0000, v241
	v_pk_add_f32 v[122:123], v[122:123], v[154:155]
	v_lshlrev_b32_e32 v156, 16, v242
	v_and_b32_e32 v157, 0xffff0000, v242
	v_pk_add_f32 v[124:125], v[124:125], v[156:157]
	v_lshlrev_b32_e32 v158, 16, v243
	v_and_b32_e32 v159, 0xffff0000, v243
	v_pk_add_f32 v[126:127], v[126:127], v[158:159]
	v_cvt_pk_bf16_f32 v120, v120, v121
	v_cvt_pk_bf16_f32 v121, v122, v123
	v_cvt_pk_bf16_f32 v122, v124, v125
	v_cvt_pk_bf16_f32 v123, v126, v127
	global_load_dwordx4 v[172:175], v[160:161], off offset:256
	v_lshl_add_u64 v[160:161], v[160:161], 0, s[6:7]
	s_waitcnt vmcnt(4)
	v_lshlrev_b32_e32 v152, 16, v176
	v_and_b32_e32 v153, 0xffff0000, v176
	v_pk_mul_f32 v[116:117], v[116:117], v[152:153]
	v_lshlrev_b32_e32 v154, 16, v177
	v_and_b32_e32 v155, 0xffff0000, v177
	v_pk_mul_f32 v[118:119], v[118:119], v[154:155]
	v_lshlrev_b32_e32 v156, 16, v178
	v_and_b32_e32 v157, 0xffff0000, v178
	v_pk_mul_f32 v[112:113], v[112:113], v[156:157]
	v_lshlrev_b32_e32 v158, 16, v179
	v_and_b32_e32 v159, 0xffff0000, v179
	v_pk_mul_f32 v[114:115], v[114:115], v[158:159]
	v_lshlrev_b32_e32 v152, 16, v244
	v_and_b32_e32 v153, 0xffff0000, v244
	v_pk_add_f32 v[116:117], v[116:117], v[152:153]
	v_lshlrev_b32_e32 v154, 16, v245
	v_and_b32_e32 v155, 0xffff0000, v245
	v_pk_add_f32 v[118:119], v[118:119], v[154:155]
	v_lshlrev_b32_e32 v156, 16, v246
	v_and_b32_e32 v157, 0xffff0000, v246
	v_pk_add_f32 v[112:113], v[112:113], v[156:157]
	v_lshlrev_b32_e32 v158, 16, v247
	v_and_b32_e32 v159, 0xffff0000, v247
	v_pk_add_f32 v[114:115], v[114:115], v[158:159]
	v_cvt_pk_bf16_f32 v116, v116, v117
	v_cvt_pk_bf16_f32 v117, v118, v119
	v_cvt_pk_bf16_f32 v118, v112, v113
	v_cvt_pk_bf16_f32 v119, v114, v115
	global_load_dwordx4 v[176:179], v[160:161], off
	s_waitcnt vmcnt(4)
	v_lshlrev_b32_e32 v152, 16, v180
	v_and_b32_e32 v153, 0xffff0000, v180
	v_pk_mul_f32 v[108:109], v[108:109], v[152:153]
	v_lshlrev_b32_e32 v154, 16, v181
	v_and_b32_e32 v155, 0xffff0000, v181
	v_pk_mul_f32 v[110:111], v[110:111], v[154:155]
	v_lshlrev_b32_e32 v156, 16, v182
	v_and_b32_e32 v157, 0xffff0000, v182
	v_pk_mul_f32 v[104:105], v[104:105], v[156:157]
	v_lshlrev_b32_e32 v158, 16, v183
	v_and_b32_e32 v159, 0xffff0000, v183
	v_pk_mul_f32 v[106:107], v[106:107], v[158:159]
	v_lshlrev_b32_e32 v152, 16, v248
	v_and_b32_e32 v153, 0xffff0000, v248
	v_pk_add_f32 v[108:109], v[108:109], v[152:153]
	v_lshlrev_b32_e32 v154, 16, v249
	v_and_b32_e32 v155, 0xffff0000, v249
	v_pk_add_f32 v[110:111], v[110:111], v[154:155]
	v_lshlrev_b32_e32 v156, 16, v250
	v_and_b32_e32 v157, 0xffff0000, v250
	v_pk_add_f32 v[104:105], v[104:105], v[156:157]
	v_lshlrev_b32_e32 v158, 16, v251
	v_and_b32_e32 v159, 0xffff0000, v251
	v_pk_add_f32 v[106:107], v[106:107], v[158:159]
	v_cvt_pk_bf16_f32 v108, v108, v109
	v_cvt_pk_bf16_f32 v109, v110, v111
	v_cvt_pk_bf16_f32 v110, v104, v105
	v_cvt_pk_bf16_f32 v111, v106, v107
	global_load_dwordx4 v[180:183], v[160:161], off offset:256
	v_lshl_add_u64 v[160:161], v[160:161], 0, s[52:53]
	s_waitcnt vmcnt(4)
; __device__ __forceinline__ u32x4 pack8(const f32x4 a, const f32x4 b) { u32x4 w; w.x = cvt_pk_bf16(a[0], a[1]); w.y = cvt_pk_bf16(a[2], a[3]); w.z = cvt_pk_bf16(b[0], b[1]); w.w = cvt_pk_bf16(b[2], b[3]); return w; }
; #define EPI_ROWLOOP _Pragma("unroll") for (int ai = 0; ai < 2; ++ai) _Pragma("unroll") for (int m = 0; m < 4; ++m)
;     __device__ __forceinline__ void operator()(const f32x4 (&acc)[2][2][4][2], const Unit& u, int wr, int wc, int fr, int fq) const {
;         const int row0 = u.pm * BM + wr * 64 + fr, c0 = u.pn * 256 + wc * 32 + 8 * fq;
;         EPI_ROWLOOP { const int r = row0 + ai * HALF + m * 16;
; #pragma unroll
;             for (int bj = 0; bj < 2; ++bj) { const int c = c0 + bj * HALF; f32x4 g0, g1; unpack8(*(const u32x4*)(GATES + (size_t)r * 2048 + (u.sel ? 1024 : 0) + c), g0, g1);
;                 f32x4 v0 = acc[ai][bj][m][0] * g0, v1 = acc[ai][bj][m][1] * g1;
;                 if (u.sel) { f32x4 t0, t1; unpack8(*(const u32x4*)(T + (size_t)r * 1024 + c), t0, t1); v0 += t0; v1 += t1; *(u32x4*)(MIX + (size_t)r * 1024 + c) = pack8(v0, v1); }
;                 else *(u32x4*)(T + (size_t)r * 1024 + c) = pack8(v0, v1); } }
;     }
	v_lshlrev_b32_e32 v152, 16, v184
	v_and_b32_e32 v153, 0xffff0000, v184
	v_pk_mul_f32 v[100:101], v[100:101], v[152:153]
	v_lshlrev_b32_e32 v154, 16, v185
	v_and_b32_e32 v155, 0xffff0000, v185
	v_pk_mul_f32 v[102:103], v[102:103], v[154:155]
	v_lshlrev_b32_e32 v156, 16, v186
	v_and_b32_e32 v157, 0xffff0000, v186
	v_pk_mul_f32 v[96:97], v[96:97], v[156:157]
	v_lshlrev_b32_e32 v158, 16, v187
	v_and_b32_e32 v159, 0xffff0000, v187
	v_pk_mul_f32 v[98:99], v[98:99], v[158:159]
	v_lshlrev_b32_e32 v152, 16, v128
	v_and_b32_e32 v153, 0xffff0000, v128
	v_pk_add_f32 v[100:101], v[100:101], v[152:153]
	v_lshlrev_b32_e32 v154, 16, v129
	v_and_b32_e32 v155, 0xffff0000, v129
	v_pk_add_f32 v[102:103], v[102:103], v[154:155]
	v_lshlrev_b32_e32 v156, 16, v130
	v_and_b32_e32 v157, 0xffff0000, v130
	v_pk_add_f32 v[96:97], v[96:97], v[156:157]
	v_lshlrev_b32_e32 v158, 16, v131
	v_and_b32_e32 v159, 0xffff0000, v131
	v_pk_add_f32 v[98:99], v[98:99], v[158:159]
	v_cvt_pk_bf16_f32 v100, v100, v101
	v_cvt_pk_bf16_f32 v101, v102, v103
	v_cvt_pk_bf16_f32 v102, v96, v97
	v_cvt_pk_bf16_f32 v103, v98, v99
	global_load_dwordx4 v[184:187], v[160:161], off
	s_waitcnt vmcnt(4)
	v_lshlrev_b32_e32 v152, 16, v188
	v_and_b32_e32 v153, 0xffff0000, v188
	v_pk_mul_f32 v[92:93], v[92:93], v[152:153]
	v_lshlrev_b32_e32 v154, 16, v189
	v_and_b32_e32 v155, 0xffff0000, v189
	v_pk_mul_f32 v[94:95], v[94:95], v[154:155]
	v_lshlrev_b32_e32 v156, 16, v190
	v_and_b32_e32 v157, 0xffff0000, v190
	v_pk_mul_f32 v[88:89], v[88:89], v[156:157]
	v_lshlrev_b32_e32 v158, 16, v191
	v_and_b32_e32 v159, 0xffff0000, v191
	v_pk_mul_f32 v[90:91], v[90:91], v[158:159]
	v_lshlrev_b32_e32 v152, 16, v148
	v_and_b32_e32 v153, 0xffff0000, v148
	v_pk_add_f32 v[92:93], v[92:93], v[152:153]
	v_lshlrev_b32_e32 v154, 16, v149
	v_and_b32_e32 v155, 0xffff0000, v149
	v_pk_add_f32 v[94:95], v[94:95], v[154:155]
	v_lshlrev_b32_e32 v156, 16, v150
	v_and_b32_e32 v157, 0xffff0000, v150
	v_pk_add_f32 v[88:89], v[88:89], v[156:157]
	v_lshlrev_b32_e32 v158, 16, v151
	v_and_b32_e32 v159, 0xffff0000, v151
	v_pk_add_f32 v[90:91], v[90:91], v[158:159]
	v_cvt_pk_bf16_f32 v92, v92, v93
	v_cvt_pk_bf16_f32 v93, v94, v95
	v_cvt_pk_bf16_f32 v94, v88, v89
	v_cvt_pk_bf16_f32 v95, v90, v91
	global_load_dwordx4 v[188:191], v[160:161], off offset:256
	v_lshl_add_u64 v[160:161], v[160:161], 0, s[6:7]
	s_waitcnt vmcnt(4)
	v_lshlrev_b32_e32 v152, 16, v192
	v_and_b32_e32 v153, 0xffff0000, v192
	v_pk_mul_f32 v[84:85], v[84:85], v[152:153]
	v_lshlrev_b32_e32 v154, 16, v193
	v_and_b32_e32 v155, 0xffff0000, v193
	v_pk_mul_f32 v[86:87], v[86:87], v[154:155]
	v_lshlrev_b32_e32 v156, 16, v194
	v_and_b32_e32 v157, 0xffff0000, v194
	v_pk_mul_f32 v[80:81], v[80:81], v[156:157]
	v_lshlrev_b32_e32 v158, 16, v195
	v_and_b32_e32 v159, 0xffff0000, v195
	v_pk_mul_f32 v[82:83], v[82:83], v[158:159]
	v_lshlrev_b32_e32 v152, 16, v172
	v_and_b32_e32 v153, 0xffff0000, v172
	v_pk_add_f32 v[84:85], v[84:85], v[152:153]
	v_lshlrev_b32_e32 v154, 16, v173
	v_and_b32_e32 v155, 0xffff0000, v173
	v_pk_add_f32 v[86:87], v[86:87], v[154:155]
	v_lshlrev_b32_e32 v156, 16, v174
	v_and_b32_e32 v157, 0xffff0000, v174
	v_pk_add_f32 v[80:81], v[80:81], v[156:157]
	v_lshlrev_b32_e32 v158, 16, v175
	v_and_b32_e32 v159, 0xffff0000, v175
	v_pk_add_f32 v[82:83], v[82:83], v[158:159]
	v_cvt_pk_bf16_f32 v84, v84, v85
	v_cvt_pk_bf16_f32 v85, v86, v87
	v_cvt_pk_bf16_f32 v86, v80, v81
	v_cvt_pk_bf16_f32 v87, v82, v83
	global_load_dwordx4 v[192:195], v[160:161], off
	s_waitcnt vmcnt(4)
	v_lshlrev_b32_e32 v152, 16, v196
	v_and_b32_e32 v153, 0xffff0000, v196
	v_pk_mul_f32 v[76:77], v[76:77], v[152:153]
	v_lshlrev_b32_e32 v154, 16, v197
	v_and_b32_e32 v155, 0xffff0000, v197
	v_pk_mul_f32 v[78:79], v[78:79], v[154:155]
	v_lshlrev_b32_e32 v156, 16, v198
	v_and_b32_e32 v157, 0xffff0000, v198
	v_pk_mul_f32 v[72:73], v[72:73], v[156:157]
	v_lshlrev_b32_e32 v158, 16, v199
	v_and_b32_e32 v159, 0xffff0000, v199
	v_pk_mul_f32 v[74:75], v[74:75], v[158:159]
	v_lshlrev_b32_e32 v152, 16, v176
	v_and_b32_e32 v153, 0xffff0000, v176
	v_pk_add_f32 v[76:77], v[76:77], v[152:153]
	v_lshlrev_b32_e32 v154, 16, v177
	v_and_b32_e32 v155, 0xffff0000, v177
	v_pk_add_f32 v[78:79], v[78:79], v[154:155]
	v_lshlrev_b32_e32 v156, 16, v178
	v_and_b32_e32 v157, 0xffff0000, v178
	v_pk_add_f32 v[72:73], v[72:73], v[156:157]
	v_lshlrev_b32_e32 v158, 16, v179
	v_and_b32_e32 v159, 0xffff0000, v179
	v_pk_add_f32 v[74:75], v[74:75], v[158:159]
	v_cvt_pk_bf16_f32 v76, v76, v77
	v_cvt_pk_bf16_f32 v77, v78, v79
	v_cvt_pk_bf16_f32 v78, v72, v73
	v_cvt_pk_bf16_f32 v79, v74, v75
	global_load_dwordx4 v[196:199], v[160:161], off offset:256
	v_lshl_add_u64 v[160:161], v[160:161], 0, s[6:7]
	s_waitcnt vmcnt(4)
	v_lshlrev_b32_e32 v152, 16, v202
	v_and_b32_e32 v153, 0xffff0000, v202
	v_pk_mul_f32 v[68:69], v[68:69], v[152:153]
	v_lshlrev_b32_e32 v154, 16, v203
	v_and_b32_e32 v155, 0xffff0000, v203
	v_pk_mul_f32 v[70:71], v[70:71], v[154:155]
	v_lshlrev_b32_e32 v156, 16, v204
	v_and_b32_e32 v157, 0xffff0000, v204
	v_pk_mul_f32 v[64:65], v[64:65], v[156:157]
	v_lshlrev_b32_e32 v158, 16, v205
	v_and_b32_e32 v159, 0xffff0000, v205
	v_pk_mul_f32 v[66:67], v[66:67], v[158:159]
	v_lshlrev_b32_e32 v152, 16, v180
	v_and_b32_e32 v153, 0xffff0000, v180
	v_pk_add_f32 v[68:69], v[68:69], v[152:153]
	v_lshlrev_b32_e32 v154, 16, v181
	v_and_b32_e32 v155, 0xffff0000, v181
	v_pk_add_f32 v[70:71], v[70:71], v[154:155]
	v_lshlrev_b32_e32 v156, 16, v182
	v_and_b32_e32 v157, 0xffff0000, v182
	v_pk_add_f32 v[64:65], v[64:65], v[156:157]
	v_lshlrev_b32_e32 v158, 16, v183
	v_and_b32_e32 v159, 0xffff0000, v183
	v_pk_add_f32 v[66:67], v[66:67], v[158:159]
	v_cvt_pk_bf16_f32 v68, v68, v69
	v_cvt_pk_bf16_f32 v69, v70, v71
	v_cvt_pk_bf16_f32 v70, v64, v65
	v_cvt_pk_bf16_f32 v71, v66, v67
	global_load_dwordx4 v[202:205], v[160:161], off
	s_waitcnt vmcnt(4)
; __device__ __forceinline__ u32x4 pack8(const f32x4 a, const f32x4 b) { u32x4 w; w.x = cvt_pk_bf16(a[0], a[1]); w.y = cvt_pk_bf16(a[2], a[3]); w.z = cvt_pk_bf16(b[0], b[1]); w.w = cvt_pk_bf16(b[2], b[3]); return w; }
; #define EPI_ROWLOOP _Pragma("unroll") for (int ai = 0; ai < 2; ++ai) _Pragma("unroll") for (int m = 0; m < 4; ++m)
;     __device__ __forceinline__ void operator()(const f32x4 (&acc)[2][2][4][2], const Unit& u, int wr, int wc, int fr, int fq) const {
;         const int row0 = u.pm * BM + wr * 64 + fr, c0 = u.pn * 256 + wc * 32 + 8 * fq;
;         EPI_ROWLOOP { const int r = row0 + ai * HALF + m * 16;
; #pragma unroll
;             for (int bj = 0; bj < 2; ++bj) { const int c = c0 + bj * HALF; f32x4 g0, g1; unpack8(*(const u32x4*)(GATES + (size_t)r * 2048 + (u.sel ? 1024 : 0) + c), g0, g1);
;                 f32x4 v0 = acc[ai][bj][m][0] * g0, v1 = acc[ai][bj][m][1] * g1;
;                 if (u.sel) { f32x4 t0, t1; unpack8(*(const u32x4*)(T + (size_t)r * 1024 + c), t0, t1); v0 += t0; v1 += t1; *(u32x4*)(MIX + (size_t)r * 1024 + c) = pack8(v0, v1); }
;                 else *(u32x4*)(T + (size_t)r * 1024 + c) = pack8(v0, v1); } }
;     }
	v_lshlrev_b32_e32 v152, 16, v206
	v_and_b32_e32 v153, 0xffff0000, v206
	v_pk_mul_f32 v[60:61], v[60:61], v[152:153]
	v_lshlrev_b32_e32 v154, 16, v207
	v_and_b32_e32 v155, 0xffff0000, v207
	v_pk_mul_f32 v[62:63], v[62:63], v[154:155]
	v_lshlrev_b32_e32 v156, 16, v208
	v_and_b32_e32 v157, 0xffff0000, v208
	v_pk_mul_f32 v[56:57], v[56:57], v[156:157]
	v_lshlrev_b32_e32 v158, 16, v209
	v_and_b32_e32 v159, 0xffff0000, v209
	v_pk_mul_f32 v[58:59], v[58:59], v[158:159]
	v_lshlrev_b32_e32 v152, 16, v184
	v_and_b32_e32 v153, 0xffff0000, v184
	v_pk_add_f32 v[60:61], v[60:61], v[152:153]
	v_lshlrev_b32_e32 v154, 16, v185
	v_and_b32_e32 v155, 0xffff0000, v185
	v_pk_add_f32 v[62:63], v[62:63], v[154:155]
	v_lshlrev_b32_e32 v156, 16, v186
	v_and_b32_e32 v157, 0xffff0000, v186
	v_pk_add_f32 v[56:57], v[56:57], v[156:157]
	v_lshlrev_b32_e32 v158, 16, v187
	v_and_b32_e32 v159, 0xffff0000, v187
	v_pk_add_f32 v[58:59], v[58:59], v[158:159]
	v_cvt_pk_bf16_f32 v60, v60, v61
	v_cvt_pk_bf16_f32 v61, v62, v63
	v_cvt_pk_bf16_f32 v62, v56, v57
	v_cvt_pk_bf16_f32 v63, v58, v59
	global_load_dwordx4 v[206:209], v[160:161], off offset:256
	v_lshl_add_u64 v[160:161], v[160:161], 0, s[6:7]
	s_waitcnt vmcnt(4)
	v_lshlrev_b32_e32 v152, 16, v210
	v_and_b32_e32 v153, 0xffff0000, v210
	v_pk_mul_f32 v[52:53], v[52:53], v[152:153]
	v_lshlrev_b32_e32 v154, 16, v211
	v_and_b32_e32 v155, 0xffff0000, v211
	v_pk_mul_f32 v[54:55], v[54:55], v[154:155]
	v_lshlrev_b32_e32 v156, 16, v212
	v_and_b32_e32 v157, 0xffff0000, v212
	v_pk_mul_f32 v[48:49], v[48:49], v[156:157]
	v_lshlrev_b32_e32 v158, 16, v213
	v_and_b32_e32 v159, 0xffff0000, v213
	v_pk_mul_f32 v[50:51], v[50:51], v[158:159]
	v_lshlrev_b32_e32 v152, 16, v188
	v_and_b32_e32 v153, 0xffff0000, v188
	v_pk_add_f32 v[52:53], v[52:53], v[152:153]
	v_lshlrev_b32_e32 v154, 16, v189
	v_and_b32_e32 v155, 0xffff0000, v189
	v_pk_add_f32 v[54:55], v[54:55], v[154:155]
	v_lshlrev_b32_e32 v156, 16, v190
	v_and_b32_e32 v157, 0xffff0000, v190
	v_pk_add_f32 v[48:49], v[48:49], v[156:157]
	v_lshlrev_b32_e32 v158, 16, v191
	v_and_b32_e32 v159, 0xffff0000, v191
	v_pk_add_f32 v[50:51], v[50:51], v[158:159]
	v_cvt_pk_bf16_f32 v52, v52, v53
	v_cvt_pk_bf16_f32 v53, v54, v55
	v_cvt_pk_bf16_f32 v54, v48, v49
	v_cvt_pk_bf16_f32 v55, v50, v51
	global_load_dwordx4 v[210:213], v[160:161], off
	s_waitcnt vmcnt(4)
	v_lshlrev_b32_e32 v152, 16, v214
	v_and_b32_e32 v153, 0xffff0000, v214
	v_pk_mul_f32 v[44:45], v[44:45], v[152:153]
	v_lshlrev_b32_e32 v154, 16, v215
	v_and_b32_e32 v155, 0xffff0000, v215
	v_pk_mul_f32 v[46:47], v[46:47], v[154:155]
	v_lshlrev_b32_e32 v156, 16, v216
	v_and_b32_e32 v157, 0xffff0000, v216
	v_pk_mul_f32 v[40:41], v[40:41], v[156:157]
	v_lshlrev_b32_e32 v158, 16, v217
	v_and_b32_e32 v159, 0xffff0000, v217
	v_pk_mul_f32 v[42:43], v[42:43], v[158:159]
	v_lshlrev_b32_e32 v152, 16, v192
	v_and_b32_e32 v153, 0xffff0000, v192
	v_pk_add_f32 v[44:45], v[44:45], v[152:153]
	v_lshlrev_b32_e32 v154, 16, v193
	v_and_b32_e32 v155, 0xffff0000, v193
	v_pk_add_f32 v[46:47], v[46:47], v[154:155]
	v_lshlrev_b32_e32 v156, 16, v194
	v_and_b32_e32 v157, 0xffff0000, v194
	v_pk_add_f32 v[40:41], v[40:41], v[156:157]
	v_lshlrev_b32_e32 v158, 16, v195
	v_and_b32_e32 v159, 0xffff0000, v195
	v_pk_add_f32 v[42:43], v[42:43], v[158:159]
	v_cvt_pk_bf16_f32 v44, v44, v45
	v_cvt_pk_bf16_f32 v45, v46, v47
	v_cvt_pk_bf16_f32 v46, v40, v41
	v_cvt_pk_bf16_f32 v47, v42, v43
	global_load_dwordx4 v[214:217], v[160:161], off offset:256
	s_waitcnt vmcnt(4)
	v_lshlrev_b32_e32 v152, 16, v218
	v_and_b32_e32 v153, 0xffff0000, v218
	v_pk_mul_f32 v[36:37], v[36:37], v[152:153]
	v_lshlrev_b32_e32 v154, 16, v219
	v_and_b32_e32 v155, 0xffff0000, v219
	v_pk_mul_f32 v[38:39], v[38:39], v[154:155]
	v_lshlrev_b32_e32 v156, 16, v220
	v_and_b32_e32 v157, 0xffff0000, v220
	v_pk_mul_f32 v[32:33], v[32:33], v[156:157]
	v_lshlrev_b32_e32 v158, 16, v221
	v_and_b32_e32 v159, 0xffff0000, v221
	v_pk_mul_f32 v[34:35], v[34:35], v[158:159]
	v_lshlrev_b32_e32 v152, 16, v196
	v_and_b32_e32 v153, 0xffff0000, v196
	v_pk_add_f32 v[36:37], v[36:37], v[152:153]
	v_lshlrev_b32_e32 v154, 16, v197
	v_and_b32_e32 v155, 0xffff0000, v197
	v_pk_add_f32 v[38:39], v[38:39], v[154:155]
	v_lshlrev_b32_e32 v156, 16, v198
	v_and_b32_e32 v157, 0xffff0000, v198
	v_pk_add_f32 v[32:33], v[32:33], v[156:157]
	v_lshlrev_b32_e32 v158, 16, v199
	v_and_b32_e32 v159, 0xffff0000, v199
	v_pk_add_f32 v[34:35], v[34:35], v[158:159]
	v_cvt_pk_bf16_f32 v36, v36, v37
	v_cvt_pk_bf16_f32 v37, v38, v39
	v_cvt_pk_bf16_f32 v38, v32, v33
	v_cvt_pk_bf16_f32 v39, v34, v35
	s_waitcnt vmcnt(3)
	v_lshlrev_b32_e32 v152, 16, v222
	v_and_b32_e32 v153, 0xffff0000, v222
	v_pk_mul_f32 v[28:29], v[28:29], v[152:153]
	v_lshlrev_b32_e32 v154, 16, v223
	v_and_b32_e32 v155, 0xffff0000, v223
	v_pk_mul_f32 v[30:31], v[30:31], v[154:155]
	v_lshlrev_b32_e32 v156, 16, v224
	v_and_b32_e32 v157, 0xffff0000, v224
	v_pk_mul_f32 v[24:25], v[24:25], v[156:157]
	v_lshlrev_b32_e32 v158, 16, v225
	v_and_b32_e32 v159, 0xffff0000, v225
	v_pk_mul_f32 v[26:27], v[26:27], v[158:159]
	v_lshlrev_b32_e32 v152, 16, v202
	v_and_b32_e32 v153, 0xffff0000, v202
	v_pk_add_f32 v[28:29], v[28:29], v[152:153]
	v_lshlrev_b32_e32 v154, 16, v203
	v_and_b32_e32 v155, 0xffff0000, v203
	v_pk_add_f32 v[30:31], v[30:31], v[154:155]
	v_lshlrev_b32_e32 v156, 16, v204
	v_and_b32_e32 v157, 0xffff0000, v204
	v_pk_add_f32 v[24:25], v[24:25], v[156:157]
	v_lshlrev_b32_e32 v158, 16, v205
	v_and_b32_e32 v159, 0xffff0000, v205
	v_pk_add_f32 v[26:27], v[26:27], v[158:159]
	v_cvt_pk_bf16_f32 v28, v28, v29
	v_cvt_pk_bf16_f32 v29, v30, v31
	v_cvt_pk_bf16_f32 v30, v24, v25
	v_cvt_pk_bf16_f32 v31, v26, v27
	s_waitcnt vmcnt(2)
; __device__ __forceinline__ u32x4 pack8(const f32x4 a, const f32x4 b) { u32x4 w; w.x = cvt_pk_bf16(a[0], a[1]); w.y = cvt_pk_bf16(a[2], a[3]); w.z = cvt_pk_bf16(b[0], b[1]); w.w = cvt_pk_bf16(b[2], b[3]); return w; }
; #define EPI_ROWLOOP _Pragma("unroll") for (int ai = 0; ai < 2; ++ai) _Pragma("unroll") for (int m = 0; m < 4; ++m)
;     __device__ __forceinline__ void operator()(const f32x4 (&acc)[2][2][4][2], const Unit& u, int wr, int wc, int fr, int fq) const {
;         const int row0 = u.pm * BM + wr * 64 + fr, c0 = u.pn * 256 + wc * 32 + 8 * fq;
;         EPI_ROWLOOP { const int r = row0 + ai * HALF + m * 16;
; #pragma unroll
;             for (int bj = 0; bj < 2; ++bj) { const int c = c0 + bj * HALF; f32x4 g0, g1; unpack8(*(const u32x4*)(GATES + (size_t)r * 2048 + (u.sel ? 1024 : 0) + c), g0, g1);
;                 f32x4 v0 = acc[ai][bj][m][0] * g0, v1 = acc[ai][bj][m][1] * g1;
;                 if (u.sel) { f32x4 t0, t1; unpack8(*(const u32x4*)(T + (size_t)r * 1024 + c), t0, t1); v0 += t0; v1 += t1; *(u32x4*)(MIX + (size_t)r * 1024 + c) = pack8(v0, v1); }
;                 else *(u32x4*)(T + (size_t)r * 1024 + c) = pack8(v0, v1); } }
;     }
	v_lshlrev_b32_e32 v152, 16, v226
	v_and_b32_e32 v153, 0xffff0000, v226
	v_pk_mul_f32 v[20:21], v[20:21], v[152:153]
	v_lshlrev_b32_e32 v154, 16, v227
	v_and_b32_e32 v155, 0xffff0000, v227
	v_pk_mul_f32 v[22:23], v[22:23], v[154:155]
	v_lshlrev_b32_e32 v156, 16, v228
	v_and_b32_e32 v157, 0xffff0000, v228
	v_pk_mul_f32 v[16:17], v[16:17], v[156:157]
	v_lshlrev_b32_e32 v158, 16, v229
	v_and_b32_e32 v159, 0xffff0000, v229
	v_pk_mul_f32 v[18:19], v[18:19], v[158:159]
	v_lshlrev_b32_e32 v152, 16, v206
	v_and_b32_e32 v153, 0xffff0000, v206
	v_pk_add_f32 v[20:21], v[20:21], v[152:153]
	v_lshlrev_b32_e32 v154, 16, v207
	v_and_b32_e32 v155, 0xffff0000, v207
	v_pk_add_f32 v[22:23], v[22:23], v[154:155]
	v_lshlrev_b32_e32 v156, 16, v208
	v_and_b32_e32 v157, 0xffff0000, v208
	v_pk_add_f32 v[16:17], v[16:17], v[156:157]
	v_lshlrev_b32_e32 v158, 16, v209
	v_and_b32_e32 v159, 0xffff0000, v209
	v_pk_add_f32 v[18:19], v[18:19], v[158:159]
	v_cvt_pk_bf16_f32 v20, v20, v21
	v_cvt_pk_bf16_f32 v21, v22, v23
	v_cvt_pk_bf16_f32 v22, v16, v17
	v_cvt_pk_bf16_f32 v23, v18, v19
	s_waitcnt vmcnt(1)
	v_lshlrev_b32_e32 v152, 16, v230
	v_and_b32_e32 v153, 0xffff0000, v230
	v_pk_mul_f32 v[12:13], v[12:13], v[152:153]
	v_lshlrev_b32_e32 v154, 16, v231
	v_and_b32_e32 v155, 0xffff0000, v231
	v_pk_mul_f32 v[14:15], v[14:15], v[154:155]
	v_lshlrev_b32_e32 v156, 16, v232
	v_and_b32_e32 v157, 0xffff0000, v232
	v_pk_mul_f32 v[8:9], v[8:9], v[156:157]
	v_lshlrev_b32_e32 v158, 16, v233
	v_and_b32_e32 v159, 0xffff0000, v233
	v_pk_mul_f32 v[10:11], v[10:11], v[158:159]
	v_lshlrev_b32_e32 v152, 16, v210
	v_and_b32_e32 v153, 0xffff0000, v210
	v_pk_add_f32 v[12:13], v[12:13], v[152:153]
	v_lshlrev_b32_e32 v154, 16, v211
	v_and_b32_e32 v155, 0xffff0000, v211
	v_pk_add_f32 v[14:15], v[14:15], v[154:155]
	v_lshlrev_b32_e32 v156, 16, v212
	v_and_b32_e32 v157, 0xffff0000, v212
	v_pk_add_f32 v[8:9], v[8:9], v[156:157]
	v_lshlrev_b32_e32 v158, 16, v213
	v_and_b32_e32 v159, 0xffff0000, v213
	v_pk_add_f32 v[10:11], v[10:11], v[158:159]
	v_cvt_pk_bf16_f32 v12, v12, v13
	v_cvt_pk_bf16_f32 v13, v14, v15
	v_cvt_pk_bf16_f32 v14, v8, v9
	v_cvt_pk_bf16_f32 v15, v10, v11
	s_waitcnt vmcnt(0)
	v_lshlrev_b32_e32 v152, 16, v236
	v_and_b32_e32 v153, 0xffff0000, v236
	v_pk_mul_f32 v[4:5], v[4:5], v[152:153]
	v_lshlrev_b32_e32 v154, 16, v237
	v_and_b32_e32 v155, 0xffff0000, v237
	v_pk_mul_f32 v[6:7], v[6:7], v[154:155]
	v_lshlrev_b32_e32 v156, 16, v238
	v_and_b32_e32 v157, 0xffff0000, v238
	v_pk_mul_f32 v[0:1], v[0:1], v[156:157]
	v_lshlrev_b32_e32 v158, 16, v239
	v_and_b32_e32 v159, 0xffff0000, v239
	v_pk_mul_f32 v[2:3], v[2:3], v[158:159]
	v_lshlrev_b32_e32 v152, 16, v214
	v_and_b32_e32 v153, 0xffff0000, v214
	v_pk_add_f32 v[4:5], v[4:5], v[152:153]
	v_lshlrev_b32_e32 v154, 16, v215
	v_and_b32_e32 v155, 0xffff0000, v215
	v_pk_add_f32 v[6:7], v[6:7], v[154:155]
	v_lshlrev_b32_e32 v156, 16, v216
	v_and_b32_e32 v157, 0xffff0000, v216
	v_pk_add_f32 v[0:1], v[0:1], v[156:157]
	v_lshlrev_b32_e32 v158, 16, v217
	v_and_b32_e32 v159, 0xffff0000, v217
	v_pk_add_f32 v[2:3], v[2:3], v[158:159]
	v_cvt_pk_bf16_f32 v4, v4, v5
	v_cvt_pk_bf16_f32 v5, v6, v7
	v_cvt_pk_bf16_f32 v6, v0, v1
	v_cvt_pk_bf16_f32 v7, v2, v3
	s_mov_b64 s[6:7], 0x8000
	s_mov_b64 s[52:53], 0x28000
	global_store_dwordx4 v[164:165], v[120:123], off
	global_store_dwordx4 v[164:165], v[116:119], off offset:256
	v_lshl_add_u64 v[164:165], v[164:165], 0, s[6:7]
	global_store_dwordx4 v[164:165], v[108:111], off
	global_store_dwordx4 v[164:165], v[100:103], off offset:256
	v_lshl_add_u64 v[164:165], v[164:165], 0, s[6:7]
	global_store_dwordx4 v[164:165], v[92:95], off
	global_store_dwordx4 v[164:165], v[84:87], off offset:256
	v_lshl_add_u64 v[164:165], v[164:165], 0, s[6:7]
	global_store_dwordx4 v[164:165], v[76:79], off
	global_store_dwordx4 v[164:165], v[68:71], off offset:256
	v_lshl_add_u64 v[164:165], v[164:165], 0, s[52:53]
	global_store_dwordx4 v[164:165], v[60:63], off
	global_store_dwordx4 v[164:165], v[52:55], off offset:256
	v_lshl_add_u64 v[164:165], v[164:165], 0, s[6:7]
	global_store_dwordx4 v[164:165], v[44:47], off
	global_store_dwordx4 v[164:165], v[36:39], off offset:256
	v_lshl_add_u64 v[164:165], v[164:165], 0, s[6:7]
	global_store_dwordx4 v[164:165], v[28:31], off
	global_store_dwordx4 v[164:165], v[20:23], off offset:256
	v_lshl_add_u64 v[164:165], v[164:165], 0, s[6:7]
	global_store_dwordx4 v[164:165], v[12:15], off
	s_and_b64 vcc, exec, s[4:5]
	s_mov_b64 s[4:5], -1
	global_store_dwordx4 v[164:165], v[4:7], off offset:256
	s_branch .Lp5_done
; __device__ __forceinline__ u32x4 pack8(const f32x4 a, const f32x4 b) { u32x4 w; w.x = cvt_pk_bf16(a[0], a[1]); w.y = cvt_pk_bf16(a[2], a[3]); w.z = cvt_pk_bf16(b[0], b[1]); w.w = cvt_pk_bf16(b[2], b[3]); return w; }
; #define EPI_ROWLOOP _Pragma("unroll") for (int ai = 0; ai < 2; ++ai) _Pragma("unroll") for (int m = 0; m < 4; ++m)
;     __device__ __forceinline__ void operator()(const f32x4 (&acc)[2][2][4][2], const Unit& u, int wr, int wc, int fr, int fq) const {
;         const int row0 = u.pm * BM + wr * 64 + fr, c0 = u.pn * 256 + wc * 32 + 8 * fq;
;         EPI_ROWLOOP { const int r = row0 + ai * HALF + m * 16;
; #pragma unroll
;             for (int bj = 0; bj < 2; ++bj) { const int c = c0 + bj * HALF; f32x4 g0, g1; unpack8(*(const u32x4*)(GATES + (size_t)r * 2048 + (u.sel ? 1024 : 0) + c), g0, g1);
;                 f32x4 v0 = acc[ai][bj][m][0] * g0, v1 = acc[ai][bj][m][1] * g1;
;                 if (u.sel) { f32x4 t0, t1; unpack8(*(const u32x4*)(T + (size_t)r * 1024 + c), t0, t1); v0 += t0; v1 += t1; *(u32x4*)(MIX + (size_t)r * 1024 + c) = pack8(v0, v1); }
;                 else *(u32x4*)(T + (size_t)r * 1024 + c) = pack8(v0, v1); } }
;     }
.Lp5_sel0:
	v_lshl_add_u64 v[164:165], s[34:35], 0, v[164:165]
	s_waitcnt vmcnt(15)
	v_lshlrev_b32_e32 v152, 16, v172
	v_and_b32_e32 v153, 0xffff0000, v172
	v_pk_mul_f32 v[120:121], v[120:121], v[152:153]
	v_lshlrev_b32_e32 v154, 16, v173
	v_and_b32_e32 v155, 0xffff0000, v173
	v_pk_mul_f32 v[122:123], v[122:123], v[154:155]
	v_lshlrev_b32_e32 v156, 16, v174
	v_and_b32_e32 v157, 0xffff0000, v174
	v_pk_mul_f32 v[124:125], v[124:125], v[156:157]
	v_lshlrev_b32_e32 v158, 16, v175
	v_and_b32_e32 v159, 0xffff0000, v175
	v_pk_mul_f32 v[126:127], v[126:127], v[158:159]
	v_cvt_pk_bf16_f32 v120, v120, v121
	v_cvt_pk_bf16_f32 v121, v122, v123
	v_cvt_pk_bf16_f32 v122, v124, v125
	v_cvt_pk_bf16_f32 v123, v126, v127
	s_waitcnt vmcnt(14)
	v_lshlrev_b32_e32 v152, 16, v176
	v_and_b32_e32 v153, 0xffff0000, v176
	v_pk_mul_f32 v[116:117], v[116:117], v[152:153]
	v_lshlrev_b32_e32 v154, 16, v177
	v_and_b32_e32 v155, 0xffff0000, v177
	v_pk_mul_f32 v[118:119], v[118:119], v[154:155]
	v_lshlrev_b32_e32 v156, 16, v178
	v_and_b32_e32 v157, 0xffff0000, v178
	v_pk_mul_f32 v[112:113], v[112:113], v[156:157]
	v_lshlrev_b32_e32 v158, 16, v179
	v_and_b32_e32 v159, 0xffff0000, v179
	v_pk_mul_f32 v[114:115], v[114:115], v[158:159]
	v_cvt_pk_bf16_f32 v116, v116, v117
	v_cvt_pk_bf16_f32 v117, v118, v119
	v_cvt_pk_bf16_f32 v118, v112, v113
	v_cvt_pk_bf16_f32 v119, v114, v115
	s_waitcnt vmcnt(13)
	v_lshlrev_b32_e32 v152, 16, v180
	v_and_b32_e32 v153, 0xffff0000, v180
	v_pk_mul_f32 v[108:109], v[108:109], v[152:153]
	v_lshlrev_b32_e32 v154, 16, v181
	v_and_b32_e32 v155, 0xffff0000, v181
	v_pk_mul_f32 v[110:111], v[110:111], v[154:155]
	v_lshlrev_b32_e32 v156, 16, v182
	v_and_b32_e32 v157, 0xffff0000, v182
	v_pk_mul_f32 v[104:105], v[104:105], v[156:157]
	v_lshlrev_b32_e32 v158, 16, v183
	v_and_b32_e32 v159, 0xffff0000, v183
	v_pk_mul_f32 v[106:107], v[106:107], v[158:159]
	v_cvt_pk_bf16_f32 v108, v108, v109
	v_cvt_pk_bf16_f32 v109, v110, v111
	v_cvt_pk_bf16_f32 v110, v104, v105
	v_cvt_pk_bf16_f32 v111, v106, v107
	s_waitcnt vmcnt(12)
	v_lshlrev_b32_e32 v152, 16, v184
	v_and_b32_e32 v153, 0xffff0000, v184
	v_pk_mul_f32 v[100:101], v[100:101], v[152:153]
	v_lshlrev_b32_e32 v154, 16, v185
	v_and_b32_e32 v155, 0xffff0000, v185
	v_pk_mul_f32 v[102:103], v[102:103], v[154:155]
	v_lshlrev_b32_e32 v156, 16, v186
	v_and_b32_e32 v157, 0xffff0000, v186
	v_pk_mul_f32 v[96:97], v[96:97], v[156:157]
	v_lshlrev_b32_e32 v158, 16, v187
	v_and_b32_e32 v159, 0xffff0000, v187
	v_pk_mul_f32 v[98:99], v[98:99], v[158:159]
	v_cvt_pk_bf16_f32 v100, v100, v101
	v_cvt_pk_bf16_f32 v101, v102, v103
	v_cvt_pk_bf16_f32 v102, v96, v97
	v_cvt_pk_bf16_f32 v103, v98, v99
	s_waitcnt vmcnt(11)
	v_lshlrev_b32_e32 v152, 16, v188
	v_and_b32_e32 v153, 0xffff0000, v188
	v_pk_mul_f32 v[92:93], v[92:93], v[152:153]
	v_lshlrev_b32_e32 v154, 16, v189
	v_and_b32_e32 v155, 0xffff0000, v189
	v_pk_mul_f32 v[94:95], v[94:95], v[154:155]
	v_lshlrev_b32_e32 v156, 16, v190
	v_and_b32_e32 v157, 0xffff0000, v190
	v_pk_mul_f32 v[88:89], v[88:89], v[156:157]
	v_lshlrev_b32_e32 v158, 16, v191
	v_and_b32_e32 v159, 0xffff0000, v191
	v_pk_mul_f32 v[90:91], v[90:91], v[158:159]
	v_cvt_pk_bf16_f32 v92, v92, v93
	v_cvt_pk_bf16_f32 v93, v94, v95
	v_cvt_pk_bf16_f32 v94, v88, v89
	v_cvt_pk_bf16_f32 v95, v90, v91
	s_waitcnt vmcnt(10)
	v_lshlrev_b32_e32 v152, 16, v192
	v_and_b32_e32 v153, 0xffff0000, v192
	v_pk_mul_f32 v[84:85], v[84:85], v[152:153]
	v_lshlrev_b32_e32 v154, 16, v193
	v_and_b32_e32 v155, 0xffff0000, v193
	v_pk_mul_f32 v[86:87], v[86:87], v[154:155]
	v_lshlrev_b32_e32 v156, 16, v194
	v_and_b32_e32 v157, 0xffff0000, v194
	v_pk_mul_f32 v[80:81], v[80:81], v[156:157]
	v_lshlrev_b32_e32 v158, 16, v195
	v_and_b32_e32 v159, 0xffff0000, v195
	v_pk_mul_f32 v[82:83], v[82:83], v[158:159]
	v_cvt_pk_bf16_f32 v84, v84, v85
	v_cvt_pk_bf16_f32 v85, v86, v87
	v_cvt_pk_bf16_f32 v86, v80, v81
	v_cvt_pk_bf16_f32 v87, v82, v83
	s_waitcnt vmcnt(9)
	v_lshlrev_b32_e32 v152, 16, v196
	v_and_b32_e32 v153, 0xffff0000, v196
	v_pk_mul_f32 v[76:77], v[76:77], v[152:153]
	v_lshlrev_b32_e32 v154, 16, v197
	v_and_b32_e32 v155, 0xffff0000, v197
	v_pk_mul_f32 v[78:79], v[78:79], v[154:155]
	v_lshlrev_b32_e32 v156, 16, v198
	v_and_b32_e32 v157, 0xffff0000, v198
	v_pk_mul_f32 v[72:73], v[72:73], v[156:157]
	v_lshlrev_b32_e32 v158, 16, v199
	v_and_b32_e32 v159, 0xffff0000, v199
	v_pk_mul_f32 v[74:75], v[74:75], v[158:159]
	v_cvt_pk_bf16_f32 v76, v76, v77
	v_cvt_pk_bf16_f32 v77, v78, v79
	v_cvt_pk_bf16_f32 v78, v72, v73
	v_cvt_pk_bf16_f32 v79, v74, v75
	s_waitcnt vmcnt(8)
	v_lshlrev_b32_e32 v152, 16, v202
	v_and_b32_e32 v153, 0xffff0000, v202
	v_pk_mul_f32 v[68:69], v[68:69], v[152:153]
	v_lshlrev_b32_e32 v154, 16, v203
	v_and_b32_e32 v155, 0xffff0000, v203
	v_pk_mul_f32 v[70:71], v[70:71], v[154:155]
	v_lshlrev_b32_e32 v156, 16, v204
	v_and_b32_e32 v157, 0xffff0000, v204
	v_pk_mul_f32 v[64:65], v[64:65], v[156:157]
	v_lshlrev_b32_e32 v158, 16, v205
	v_and_b32_e32 v159, 0xffff0000, v205
	v_pk_mul_f32 v[66:67], v[66:67], v[158:159]
	v_cvt_pk_bf16_f32 v68, v68, v69
	v_cvt_pk_bf16_f32 v69, v70, v71
	v_cvt_pk_bf16_f32 v70, v64, v65
	v_cvt_pk_bf16_f32 v71, v66, v67
	s_waitcnt vmcnt(7)
	v_lshlrev_b32_e32 v152, 16, v206
	v_and_b32_e32 v153, 0xffff0000, v206
	v_pk_mul_f32 v[60:61], v[60:61], v[152:153]
	v_lshlrev_b32_e32 v154, 16, v207
	v_and_b32_e32 v155, 0xffff0000, v207
	v_pk_mul_f32 v[62:63], v[62:63], v[154:155]
	v_lshlrev_b32_e32 v156, 16, v208
	v_and_b32_e32 v157, 0xffff0000, v208
	v_pk_mul_f32 v[56:57], v[56:57], v[156:157]
	v_lshlrev_b32_e32 v158, 16, v209
	v_and_b32_e32 v159, 0xffff0000, v209
	v_pk_mul_f32 v[58:59], v[58:59], v[158:159]
	v_cvt_pk_bf16_f32 v60, v60, v61
	v_cvt_pk_bf16_f32 v61, v62, v63
	v_cvt_pk_bf16_f32 v62, v56, v57
	v_cvt_pk_bf16_f32 v63, v58, v59
	s_waitcnt vmcnt(6)
; __device__ __forceinline__ u32x4 pack8(const f32x4 a, const f32x4 b) { u32x4 w; w.x = cvt_pk_bf16(a[0], a[1]); w.y = cvt_pk_bf16(a[2], a[3]); w.z = cvt_pk_bf16(b[0], b[1]); w.w = cvt_pk_bf16(b[2], b[3]); return w; }
; #define EPI_ROWLOOP _Pragma("unroll") for (int ai = 0; ai < 2; ++ai) _Pragma("unroll") for (int m = 0; m < 4; ++m)
;     __device__ __forceinline__ void operator()(const f32x4 (&acc)[2][2][4][2], const Unit& u, int wr, int wc, int fr, int fq) const {
;         const int row0 = u.pm * BM + wr * 64 + fr, c0 = u.pn * 256 + wc * 32 + 8 * fq;
;         EPI_ROWLOOP { const int r = row0 + ai * HALF + m * 16;
; #pragma unroll
;             for (int bj = 0; bj < 2; ++bj) { const int c = c0 + bj * HALF; f32x4 g0, g1; unpack8(*(const u32x4*)(GATES + (size_t)r * 2048 + (u.sel ? 1024 : 0) + c), g0, g1);
;                 f32x4 v0 = acc[ai][bj][m][0] * g0, v1 = acc[ai][bj][m][1] * g1;
;                 if (u.sel) { f32x4 t0, t1; unpack8(*(const u32x4*)(T + (size_t)r * 1024 + c), t0, t1); v0 += t0; v1 += t1; *(u32x4*)(MIX + (size_t)r * 1024 + c) = pack8(v0, v1); }
;                 else *(u32x4*)(T + (size_t)r * 1024 + c) = pack8(v0, v1); } }
;     }
	v_lshlrev_b32_e32 v152, 16, v210
	v_and_b32_e32 v153, 0xffff0000, v210
	v_pk_mul_f32 v[52:53], v[52:53], v[152:153]
	v_lshlrev_b32_e32 v154, 16, v211
	v_and_b32_e32 v155, 0xffff0000, v211
	v_pk_mul_f32 v[54:55], v[54:55], v[154:155]
	v_lshlrev_b32_e32 v156, 16, v212
	v_and_b32_e32 v157, 0xffff0000, v212
	v_pk_mul_f32 v[48:49], v[48:49], v[156:157]
	v_lshlrev_b32_e32 v158, 16, v213
	v_and_b32_e32 v159, 0xffff0000, v213
	v_pk_mul_f32 v[50:51], v[50:51], v[158:159]
	v_cvt_pk_bf16_f32 v52, v52, v53
	v_cvt_pk_bf16_f32 v53, v54, v55
	v_cvt_pk_bf16_f32 v54, v48, v49
	v_cvt_pk_bf16_f32 v55, v50, v51
	s_waitcnt vmcnt(5)
	v_lshlrev_b32_e32 v152, 16, v214
	v_and_b32_e32 v153, 0xffff0000, v214
	v_pk_mul_f32 v[44:45], v[44:45], v[152:153]
	v_lshlrev_b32_e32 v154, 16, v215
	v_and_b32_e32 v155, 0xffff0000, v215
	v_pk_mul_f32 v[46:47], v[46:47], v[154:155]
	v_lshlrev_b32_e32 v156, 16, v216
	v_and_b32_e32 v157, 0xffff0000, v216
	v_pk_mul_f32 v[40:41], v[40:41], v[156:157]
	v_lshlrev_b32_e32 v158, 16, v217
	v_and_b32_e32 v159, 0xffff0000, v217
	v_pk_mul_f32 v[42:43], v[42:43], v[158:159]
	v_cvt_pk_bf16_f32 v44, v44, v45
	v_cvt_pk_bf16_f32 v45, v46, v47
	v_cvt_pk_bf16_f32 v46, v40, v41
	v_cvt_pk_bf16_f32 v47, v42, v43
	s_waitcnt vmcnt(4)
	v_lshlrev_b32_e32 v152, 16, v218
	v_and_b32_e32 v153, 0xffff0000, v218
	v_pk_mul_f32 v[36:37], v[36:37], v[152:153]
	v_lshlrev_b32_e32 v154, 16, v219
	v_and_b32_e32 v155, 0xffff0000, v219
	v_pk_mul_f32 v[38:39], v[38:39], v[154:155]
	v_lshlrev_b32_e32 v156, 16, v220
	v_and_b32_e32 v157, 0xffff0000, v220
	v_pk_mul_f32 v[32:33], v[32:33], v[156:157]
	v_lshlrev_b32_e32 v158, 16, v221
	v_and_b32_e32 v159, 0xffff0000, v221
	v_pk_mul_f32 v[34:35], v[34:35], v[158:159]
	v_cvt_pk_bf16_f32 v36, v36, v37
	v_cvt_pk_bf16_f32 v37, v38, v39
	v_cvt_pk_bf16_f32 v38, v32, v33
	v_cvt_pk_bf16_f32 v39, v34, v35
	s_waitcnt vmcnt(3)
	v_lshlrev_b32_e32 v152, 16, v222
	v_and_b32_e32 v153, 0xffff0000, v222
	v_pk_mul_f32 v[28:29], v[28:29], v[152:153]
	v_lshlrev_b32_e32 v154, 16, v223
	v_and_b32_e32 v155, 0xffff0000, v223
	v_pk_mul_f32 v[30:31], v[30:31], v[154:155]
	v_lshlrev_b32_e32 v156, 16, v224
	v_and_b32_e32 v157, 0xffff0000, v224
	v_pk_mul_f32 v[24:25], v[24:25], v[156:157]
	v_lshlrev_b32_e32 v158, 16, v225
	v_and_b32_e32 v159, 0xffff0000, v225
	v_pk_mul_f32 v[26:27], v[26:27], v[158:159]
	v_cvt_pk_bf16_f32 v28, v28, v29
	v_cvt_pk_bf16_f32 v29, v30, v31
	v_cvt_pk_bf16_f32 v30, v24, v25
	v_cvt_pk_bf16_f32 v31, v26, v27
	s_waitcnt vmcnt(2)
	v_lshlrev_b32_e32 v152, 16, v226
	v_and_b32_e32 v153, 0xffff0000, v226
	v_pk_mul_f32 v[20:21], v[20:21], v[152:153]
	v_lshlrev_b32_e32 v154, 16, v227
	v_and_b32_e32 v155, 0xffff0000, v227
	v_pk_mul_f32 v[22:23], v[22:23], v[154:155]
	v_lshlrev_b32_e32 v156, 16, v228
	v_and_b32_e32 v157, 0xffff0000, v228
	v_pk_mul_f32 v[16:17], v[16:17], v[156:157]
	v_lshlrev_b32_e32 v158, 16, v229
	v_and_b32_e32 v159, 0xffff0000, v229
	v_pk_mul_f32 v[18:19], v[18:19], v[158:159]
	v_cvt_pk_bf16_f32 v20, v20, v21
	v_cvt_pk_bf16_f32 v21, v22, v23
	v_cvt_pk_bf16_f32 v22, v16, v17
	v_cvt_pk_bf16_f32 v23, v18, v19
	s_waitcnt vmcnt(1)
	v_lshlrev_b32_e32 v152, 16, v230
	v_and_b32_e32 v153, 0xffff0000, v230
	v_pk_mul_f32 v[12:13], v[12:13], v[152:153]
	v_lshlrev_b32_e32 v154, 16, v231
	v_and_b32_e32 v155, 0xffff0000, v231
	v_pk_mul_f32 v[14:15], v[14:15], v[154:155]
	v_lshlrev_b32_e32 v156, 16, v232
	v_and_b32_e32 v157, 0xffff0000, v232
	v_pk_mul_f32 v[8:9], v[8:9], v[156:157]
	v_lshlrev_b32_e32 v158, 16, v233
	v_and_b32_e32 v159, 0xffff0000, v233
	v_pk_mul_f32 v[10:11], v[10:11], v[158:159]
	v_cvt_pk_bf16_f32 v12, v12, v13
	v_cvt_pk_bf16_f32 v13, v14, v15
	v_cvt_pk_bf16_f32 v14, v8, v9
	v_cvt_pk_bf16_f32 v15, v10, v11
	s_waitcnt vmcnt(0)
	v_lshlrev_b32_e32 v152, 16, v236
	v_and_b32_e32 v153, 0xffff0000, v236
	v_pk_mul_f32 v[4:5], v[4:5], v[152:153]
	v_lshlrev_b32_e32 v154, 16, v237
	v_and_b32_e32 v155, 0xffff0000, v237
	v_pk_mul_f32 v[6:7], v[6:7], v[154:155]
	v_lshlrev_b32_e32 v156, 16, v238
	v_and_b32_e32 v157, 0xffff0000, v238
	v_pk_mul_f32 v[0:1], v[0:1], v[156:157]
	v_lshlrev_b32_e32 v158, 16, v239
	v_and_b32_e32 v159, 0xffff0000, v239
	v_pk_mul_f32 v[2:3], v[2:3], v[158:159]
	v_cvt_pk_bf16_f32 v4, v4, v5
	v_cvt_pk_bf16_f32 v5, v6, v7
	v_cvt_pk_bf16_f32 v6, v0, v1
	v_cvt_pk_bf16_f32 v7, v2, v3
	s_mov_b64 s[6:7], 0x8000
	s_mov_b64 s[52:53], 0x28000
	global_store_dwordx4 v[164:165], v[120:123], off
	global_store_dwordx4 v[164:165], v[116:119], off offset:256
	v_lshl_add_u64 v[164:165], v[164:165], 0, s[6:7]
	global_store_dwordx4 v[164:165], v[108:111], off
	global_store_dwordx4 v[164:165], v[100:103], off offset:256
	v_lshl_add_u64 v[164:165], v[164:165], 0, s[6:7]
	global_store_dwordx4 v[164:165], v[92:95], off
	global_store_dwordx4 v[164:165], v[84:87], off offset:256
	v_lshl_add_u64 v[164:165], v[164:165], 0, s[6:7]
	global_store_dwordx4 v[164:165], v[76:79], off
	global_store_dwordx4 v[164:165], v[68:71], off offset:256
	v_lshl_add_u64 v[164:165], v[164:165], 0, s[52:53]
	global_store_dwordx4 v[164:165], v[60:63], off
	global_store_dwordx4 v[164:165], v[52:55], off offset:256
	v_lshl_add_u64 v[164:165], v[164:165], 0, s[6:7]
	global_store_dwordx4 v[164:165], v[44:47], off
	global_store_dwordx4 v[164:165], v[36:39], off offset:256
	v_lshl_add_u64 v[164:165], v[164:165], 0, s[6:7]
	global_store_dwordx4 v[164:165], v[28:31], off
	global_store_dwordx4 v[164:165], v[20:23], off offset:256
	v_lshl_add_u64 v[164:165], v[164:165], 0, s[6:7]
	global_store_dwordx4 v[164:165], v[12:15], off
	s_and_b64 vcc, exec, s[4:5]
	s_mov_b64 s[4:5], -1
	global_store_dwordx4 v[164:165], v[4:7], off offset:256
.Lp5_done:
	s_cbranch_vccnz .LBB0_715
	s_andn2_b64 vcc, exec, s[42:43]
	s_cbranch_vccnz .LBB0_714
	s_barrier
	s_branch .LBB0_714

; __device__ __forceinline__ unsigned cvtpk(float lo, float hi) { return pg8::cvt_pk_bf16(lo, hi); }
; __device__ __forceinline__ float bf_lo(unsigned w) { return __uint_as_float(w << 16); }
; __device__ __forceinline__ float bf_hi(unsigned w) { return __uint_as_float(w & 0xffff0000u); }
; __device__ __forceinline__ void rows1_phase(const Params& p) {
;     ...
;     for (int r = gw; r < MR; r += 2 * NGW) {
;         u32x2 y[2][4]; f32x4 xv[2][4], qp[2][4];
; #pragma unroll
;         for (int q = 0; q < 2; ++q) { const size_t rr = (size_t)(r + q * NGW < MR ? r + q * NGW : r);
; #pragma unroll
;             for (int j = 0; j < 4; ++j) { y[q][j] = *((const u32x2*)(Y + rr * DM) + lane + 64 * j); xv[q][j] = *(const f32x4*)(p.x + rr * DM + 4 * lane + 256 * j); qp[q][j] = part[rr * 4 + j]; } }
; #pragma unroll
;         for (int q = 0; q < 2; ++q) { const int rq = r + q * NGW; if (rq >= MR) break; const size_t rr = (size_t)rq;
;             const f32x4 qs = (qp[q][0] + qp[q][1]) + (qp[q][2] + qp[q][3]);
;             const float rs = __builtin_amdgcn_rsqf(((qs[0] + qs[1]) + (qs[2] + qs[3])) * (1.0f / DM) + EPS);
;             f32x4 hv[4]; float s = 0.f;
; #pragma unroll
;             for (int j = 0; j < 4; ++j) { const f32x4 yv = {bf_lo(y[q][j].x), bf_hi(y[q][j].x), bf_lo(y[q][j].y), bf_hi(y[q][j].y)};
;                 hv[j] = xv[q][j] + yv * rs * gp[j]; *((u32x2*)(p.out + rr * DM) + lane + 64 * j) = (u32x2){cvtpk(hv[j][0], hv[j][1]), cvtpk(hv[j][2], hv[j][3])};
;                 s += (hv[j][0] * hv[j][0] + hv[j][1] * hv[j][1]) + (hv[j][2] * hv[j][2] + hv[j][3] * hv[j][3]); }
.LBB0_953:
	global_load_dwordx4 v[98:101], v[80:81], off offset:16
	global_load_dwordx4 v[102:105], v[80:81], off
	global_load_dwordx4 v[106:109], v[80:81], off offset:48
	global_load_dwordx4 v[110:113], v[80:81], off offset:32
	v_lshl_add_u64 v[130:131], v[72:73], 0, v[66:67]
	s_waitcnt vmcnt(12)
	v_add_co_u32_e32 v32, vcc, s7, v130
	s_waitcnt vmcnt(2)
	v_pk_add_f32 v[100:101], v[100:101], v[104:105]
	v_addc_co_u32_e32 v33, vcc, 0, v131, vcc
	global_load_dwordx2 v[132:133], v[32:33], off
	global_load_dwordx2 v[134:135], v[32:33], off offset:512
	global_load_dwordx2 v[136:137], v[32:33], off offset:1024
	global_load_dwordx2 v[138:139], v[32:33], off offset:1536
	global_load_dwordx4 v[114:117], v[78:79], off nt
	global_load_dwordx4 v[118:121], v[78:79], off offset:1024 nt
	global_load_dwordx4 v[122:125], v[78:79], off offset:2048 nt
	global_load_dwordx4 v[126:129], v[78:79], off offset:3072 nt
	v_add_u32_e32 v32, s33, v64
	v_cmp_gt_i32_e32 vcc, s3, v32
	v_pk_add_f32 v[98:99], v[98:99], v[102:103]
	s_waitcnt vmcnt(8)
	v_pk_add_f32 v[102:103], v[108:109], v[112:113]
	v_cndmask_b32_e32 v32, v64, v32, vcc
	v_ashrrev_i32_e32 v33, 31, v32
	v_lshlrev_b64 v[34:35], 11, v[32:33]
	v_lshlrev_b64 v[36:37], 12, v[32:33]
	v_lshlrev_b64 v[32:33], 6, v[32:33]
	v_lshl_add_u64 v[34:35], v[68:69], 0, v[34:35]
	v_lshl_add_u64 v[32:33], s[10:11], 0, v[32:33]
	v_lshl_add_u64 v[140:141], v[70:71], 0, v[36:37]
	global_load_dwordx4 v[48:51], v[32:33], off offset:48
	global_load_dwordx4 v[52:55], v[32:33], off offset:32
	global_load_dwordx4 v[56:59], v[32:33], off offset:16
	global_load_dwordx4 v[60:63], v[32:33], off
	global_load_dwordx4 v[44:47], v[140:141], off nt
	global_load_dwordx4 v[40:43], v[140:141], off offset:1024 nt
	global_load_dwordx2 v[90:91], v[34:35], off
	global_load_dwordx2 v[88:89], v[34:35], off offset:512
	global_load_dwordx2 v[86:87], v[34:35], off offset:1024
	global_load_dwordx2 v[84:85], v[34:35], off offset:1536
	global_load_dwordx4 v[36:39], v[140:141], off offset:2048 nt
	s_nop 0
	global_load_dwordx4 v[32:35], v[140:141], off offset:3072 nt
	v_pk_add_f32 v[104:105], v[106:107], v[110:111]
	v_pk_add_f32 v[100:101], v[102:103], v[100:101]
	v_pk_add_f32 v[98:99], v[104:105], v[98:99]
	s_waitcnt vmcnt(19)
	v_lshlrev_b32_e32 v104, 16, v133
	v_pk_mov_b32 v[102:103], v[98:99], v[100:101] op_sel:[1,0]
	v_mov_b32_e32 v99, v101
	v_pk_add_f32 v[98:99], v[102:103], v[98:99]
	v_lshlrev_b32_e32 v100, 16, v132
	v_add_f32_e32 v98, v98, v99
	v_fmamk_f32 v98, v98, 0x3a800000, v65
	v_rsq_f32_e32 v98, v98
	v_and_b32_e32 v101, 0xffff0000, v132
	v_and_b32_e32 v105, 0xffff0000, v133
	s_waitcnt vmcnt(18)
	v_lshlrev_b32_e32 v106, 16, v134
	v_and_b32_e32 v107, 0xffff0000, v134
	v_lshlrev_b32_e32 v108, 16, v135
	v_and_b32_e32 v109, 0xffff0000, v135
	v_pk_mul_f32 v[100:101], v[98:99], v[100:101] op_sel_hi:[0,1]
	v_pk_mul_f32 v[104:105], v[98:99], v[104:105] op_sel_hi:[0,1]
	v_pk_mul_f32 v[106:107], v[98:99], v[106:107] op_sel_hi:[0,1]
	v_pk_mul_f32 v[108:109], v[98:99], v[108:109] op_sel_hi:[0,1]
	s_waitcnt vmcnt(17)
	v_lshlrev_b32_e32 v110, 16, v136
	v_and_b32_e32 v111, 0xffff0000, v136
	v_lshlrev_b32_e32 v112, 16, v137
	v_and_b32_e32 v113, 0xffff0000, v137
	s_waitcnt vmcnt(15)
	v_pk_fma_f32 v[104:105], v[2:3], v[104:105], v[116:117]
	v_pk_fma_f32 v[100:101], v[0:1], v[100:101], v[114:115]
	s_waitcnt vmcnt(14)
	v_pk_fma_f32 v[108:109], v[10:11], v[108:109], v[120:121]
	v_pk_fma_f32 v[106:107], v[8:9], v[106:107], v[118:119]
	v_pk_mul_f32 v[110:111], v[98:99], v[110:111] op_sel_hi:[0,1]
	v_pk_mul_f32 v[112:113], v[98:99], v[112:113] op_sel_hi:[0,1]
	v_pk_mul_f32 v[114:115], v[104:105], v[104:105]
	v_pk_mul_f32 v[116:117], v[100:101], v[100:101]
	v_pk_mul_f32 v[118:119], v[108:109], v[108:109]
	v_pk_mul_f32 v[120:121], v[106:107], v[106:107]
	v_lshlrev_b32_e32 v132, 16, v138
	v_and_b32_e32 v133, 0xffff0000, v138
	v_lshlrev_b32_e32 v102, 16, v139
	v_and_b32_e32 v103, 0xffff0000, v139
	s_waitcnt vmcnt(13)
	v_pk_fma_f32 v[112:113], v[18:19], v[112:113], v[124:125]
	v_pk_fma_f32 v[110:111], v[16:17], v[110:111], v[122:123]
	v_pk_mov_b32 v[134:135], v[116:117], v[114:115] op_sel:[1,0]
	v_mov_b32_e32 v117, v115
	v_pk_mov_b32 v[114:115], v[120:121], v[118:119] op_sel:[1,0]
	v_mov_b32_e32 v121, v119
	v_pk_mul_f32 v[132:133], v[98:99], v[132:133] op_sel_hi:[0,1]
	v_mul_f32_e32 v122, v110, v110
	v_mul_f32_e32 v124, v112, v112
	v_pk_add_f32 v[116:117], v[116:117], v[134:135]
	v_pk_add_f32 v[114:115], v[120:121], v[114:115]
	v_pk_mul_f32 v[98:99], v[98:99], v[102:103] op_sel_hi:[0,1]
	v_pk_fma_f32 v[118:119], v[110:111], v[110:111], v[122:123] op_sel_hi:[1,1,0]
	v_pk_fma_f32 v[122:123], v[112:113], v[112:113], v[124:125] op_sel_hi:[1,1,0]
	v_pk_add_f32 v[116:117], v[116:117], v[116:117] op_sel_hi:[0,1]
	v_pk_add_f32 v[114:115], v[114:115], v[114:115] op_sel_hi:[0,1]
	s_waitcnt vmcnt(12)
	v_pk_fma_f32 v[98:99], v[26:27], v[98:99], v[128:129]
	v_pk_fma_f32 v[102:103], v[24:25], v[132:133], v[126:127]
	v_mul_f32_e32 v114, v98, v98
	v_mul_f32_e32 v118, v102, v102
	v_mul_f32_e32 v122, v103, v103
	v_mul_f32_e32 v116, v99, v99
	v_pk_add_f32 v[118:119], v[118:119], v[122:123]
	v_pk_add_f32 v[114:115], v[116:117], v[114:115]
	v_cvt_pk_bf16_f32 v121, v108, v109
	v_pk_add_f32 v[114:115], v[118:119], v[114:115]
	v_cvt_pk_bf16_f32 v118, v100, v101
	v_add_f32_e32 v114, v114, v115
	ds_bpermute_b32 v115, v92, v114
	v_cvt_pk_bf16_f32 v122, v110, v111
	v_cvt_pk_bf16_f32 v125, v98, v99
	s_waitcnt lgkmcnt(0)
	v_add_f32_e32 v114, v114, v115
	ds_bpermute_b32 v115, v93, v114
	s_waitcnt lgkmcnt(0)
	v_add_f32_e32 v116, v114, v115
	ds_bpermute_b32 v117, v94, v116
	v_lshl_add_u64 v[114:115], v[74:75], 0, v[66:67]
	s_waitcnt lgkmcnt(0)
; __device__ __forceinline__ unsigned cvtpk(float lo, float hi) { return pg8::cvt_pk_bf16(lo, hi); }
; __device__ __forceinline__ float bf_lo(unsigned w) { return __uint_as_float(w << 16); }
; __device__ __forceinline__ float bf_hi(unsigned w) { return __uint_as_float(w & 0xffff0000u); }
; __device__ __forceinline__ void rows1_phase(const Params& p) {
;     ...
;             for (int j = 0; j < 4; ++j) { const f32x4 yv = {bf_lo(y[q][j].x), bf_hi(y[q][j].x), bf_lo(y[q][j].y), bf_hi(y[q][j].y)};
;                 hv[j] = xv[q][j] + yv * rs * gp[j]; *((u32x2*)(p.out + rr * DM) + lane + 64 * j) = (u32x2){cvtpk(hv[j][0], hv[j][1]), cvtpk(hv[j][2], hv[j][3])};
;                 s += (hv[j][0] * hv[j][0] + hv[j][1] * hv[j][1]) + (hv[j][2] * hv[j][2] + hv[j][3] * hv[j][3]); }
;             const float rs2 = __builtin_amdgcn_rsqf(wave_sum(s) * (1.0f / DM) + EPS);
; #pragma unroll
;             for (int j = 0; j < 4; ++j) { const f32x4 w = hv[j] * rs2 * g2[j]; *((u32x2*)(U2 + rr * DM) + lane + 64 * j) = (u32x2){cvtpk(w[0], w[1]), cvtpk(w[2], w[3])}; } }
	v_add_f32_e32 v119, v116, v117
	ds_bpermute_b32 v120, v95, v119
	v_add_co_u32_e64 v116, s[0:1], s40, v130
	s_waitcnt lgkmcnt(0)
	v_add_f32_e32 v123, v119, v120
	ds_bpermute_b32 v124, v96, v123
	v_cvt_pk_bf16_f32 v119, v104, v105
	global_store_dwordx2 v[114:115], v[118:119], off nt
	v_addc_co_u32_e64 v117, s[0:1], 0, v131, s[0:1]
	s_waitcnt lgkmcnt(0)
	v_add_f32_e32 v126, v123, v124
	ds_bpermute_b32 v127, v97, v126
	v_cvt_pk_bf16_f32 v120, v106, v107
	v_cvt_pk_bf16_f32 v123, v112, v113
	v_cvt_pk_bf16_f32 v124, v102, v103
	global_store_dwordx2 v[114:115], v[120:121], off offset:512 nt
	global_store_dwordx2 v[114:115], v[122:123], off offset:1024 nt
	global_store_dwordx2 v[114:115], v[124:125], off offset:1536 nt
	s_waitcnt lgkmcnt(0)
	v_add_f32_e32 v118, v126, v127
	v_fmamk_f32 v118, v118, 0x3a800000, v65
	v_rsq_f32_e32 v118, v118
	s_nop 0
	v_pk_mul_f32 v[100:101], v[100:101], v[118:119] op_sel_hi:[1,0]
	v_pk_mul_f32 v[104:105], v[104:105], v[118:119] op_sel_hi:[1,0]
	v_pk_mul_f32 v[100:101], v[4:5], v[100:101]
	v_pk_mul_f32 v[104:105], v[6:7], v[104:105]
	v_cvt_pk_bf16_f32 v100, v100, v101
	v_cvt_pk_bf16_f32 v101, v104, v105
	global_store_dwordx2 v[116:117], v[100:101], off
	v_pk_mul_f32 v[100:101], v[106:107], v[118:119] op_sel_hi:[1,0]
	v_pk_mul_f32 v[104:105], v[108:109], v[118:119] op_sel_hi:[1,0]
	v_pk_mul_f32 v[100:101], v[12:13], v[100:101]
	v_pk_mul_f32 v[104:105], v[14:15], v[104:105]
	v_cvt_pk_bf16_f32 v100, v100, v101
	v_cvt_pk_bf16_f32 v101, v104, v105
	global_store_dwordx2 v[116:117], v[100:101], off offset:512
	v_pk_mul_f32 v[100:101], v[110:111], v[118:119] op_sel_hi:[1,0]
	v_pk_mul_f32 v[104:105], v[112:113], v[118:119] op_sel_hi:[1,0]
	v_pk_mul_f32 v[100:101], v[20:21], v[100:101]
	v_pk_mul_f32 v[104:105], v[22:23], v[104:105]
	v_cvt_pk_bf16_f32 v100, v100, v101
	v_cvt_pk_bf16_f32 v101, v104, v105
	global_store_dwordx2 v[116:117], v[100:101], off offset:1024
	v_pk_mul_f32 v[100:101], v[102:103], v[118:119] op_sel_hi:[1,0]
	v_pk_mul_f32 v[98:99], v[98:99], v[118:119] op_sel_hi:[1,0]
	v_pk_mul_f32 v[100:101], v[28:29], v[100:101]
	v_pk_mul_f32 v[98:99], v[30:31], v[98:99]
	v_cvt_pk_bf16_f32 v100, v100, v101
	v_cvt_pk_bf16_f32 v101, v98, v99
	global_store_dwordx2 v[116:117], v[100:101], off offset:1536
	s_and_saveexec_b64 s[0:1], vcc
	s_cbranch_execz .LBB0_952
; __device__ __forceinline__ unsigned cvtpk(float lo, float hi) { return pg8::cvt_pk_bf16(lo, hi); }
; __device__ __forceinline__ float bf_lo(unsigned w) { return __uint_as_float(w << 16); }
; __device__ __forceinline__ float bf_hi(unsigned w) { return __uint_as_float(w & 0xffff0000u); }
; __device__ __forceinline__ void rows1_phase(const Params& p) {
;     ...
;         for (int q = 0; q < 2; ++q) { const int rq = r + q * NGW; if (rq >= MR) break; const size_t rr = (size_t)rq;
;             const f32x4 qs = (qp[q][0] + qp[q][1]) + (qp[q][2] + qp[q][3]);
;             const float rs = __builtin_amdgcn_rsqf(((qs[0] + qs[1]) + (qs[2] + qs[3])) * (1.0f / DM) + EPS);
;             f32x4 hv[4]; float s = 0.f;
; #pragma unroll
;             for (int j = 0; j < 4; ++j) { const f32x4 yv = {bf_lo(y[q][j].x), bf_hi(y[q][j].x), bf_lo(y[q][j].y), bf_hi(y[q][j].y)};
;                 hv[j] = xv[q][j] + yv * rs * gp[j]; *((u32x2*)(p.out + rr * DM) + lane + 64 * j) = (u32x2){cvtpk(hv[j][0], hv[j][1]), cvtpk(hv[j][2], hv[j][3])};
;                 s += (hv[j][0] * hv[j][0] + hv[j][1] * hv[j][1]) + (hv[j][2] * hv[j][2] + hv[j][3] * hv[j][3]); }
;             const float rs2 = __builtin_amdgcn_rsqf(wave_sum(s) * (1.0f / DM) + EPS);
; #pragma unroll
;             for (int j = 0; j < 4; ++j) { const f32x4 w = hv[j] * rs2 * g2[j]; *((u32x2*)(U2 + rr * DM) + lane + 64 * j) = (u32x2){cvtpk(w[0], w[1]), cvtpk(w[2], w[3])}; } }
	s_waitcnt vmcnt(16)
	v_pk_add_f32 v[58:59], v[62:63], v[58:59]
	v_pk_add_f32 v[56:57], v[60:61], v[56:57]
	v_pk_add_f32 v[48:49], v[52:53], v[48:49]
	v_pk_add_f32 v[50:51], v[54:55], v[50:51]
	v_pk_add_f32 v[48:49], v[56:57], v[48:49]
	v_pk_add_f32 v[50:51], v[58:59], v[50:51]
	s_waitcnt vmcnt(10)
	v_lshlrev_b32_e32 v58, 16, v84
	v_pk_mov_b32 v[52:53], v[48:49], v[50:51] op_sel:[1,0]
	v_mov_b32_e32 v49, v51
	v_pk_add_f32 v[48:49], v[52:53], v[48:49]
	v_lshlrev_b32_e32 v50, 16, v90
	v_add_f32_e32 v48, v48, v49
	v_fmamk_f32 v48, v48, 0x3a800000, v65
	v_rsq_f32_e32 v48, v48
	v_and_b32_e32 v51, 0xffff0000, v90
	v_lshlrev_b32_e32 v52, 16, v91
	v_and_b32_e32 v53, 0xffff0000, v91
	v_pk_mul_f32 v[50:51], v[48:49], v[50:51] op_sel_hi:[0,1]
	v_pk_mul_f32 v[52:53], v[48:49], v[52:53] op_sel_hi:[0,1]
	v_pk_fma_f32 v[46:47], v[2:3], v[52:53], v[46:47]
	v_pk_fma_f32 v[44:45], v[0:1], v[50:51], v[44:45]
	v_pk_mul_f32 v[50:51], v[46:47], v[46:47]
	v_pk_mul_f32 v[52:53], v[44:45], v[44:45]
	v_and_b32_e32 v59, 0xffff0000, v84
	v_pk_mov_b32 v[54:55], v[52:53], v[50:51] op_sel:[1,0]
	v_mov_b32_e32 v53, v51
	v_pk_add_f32 v[50:51], v[52:53], v[54:55]
	v_lshlrev_b32_e32 v52, 16, v88
	v_and_b32_e32 v53, 0xffff0000, v88
	v_lshlrev_b32_e32 v54, 16, v89
	v_and_b32_e32 v55, 0xffff0000, v89
	v_pk_mul_f32 v[52:53], v[48:49], v[52:53] op_sel_hi:[0,1]
	v_pk_mul_f32 v[54:55], v[48:49], v[54:55] op_sel_hi:[0,1]
	v_pk_fma_f32 v[42:43], v[10:11], v[54:55], v[42:43]
	v_pk_fma_f32 v[40:41], v[8:9], v[52:53], v[40:41]
	v_pk_mul_f32 v[52:53], v[42:43], v[42:43]
	v_pk_mul_f32 v[54:55], v[40:41], v[40:41]
	v_pk_add_f32 v[50:51], v[50:51], v[50:51] op_sel_hi:[0,1]
	v_pk_mov_b32 v[56:57], v[54:55], v[52:53] op_sel:[1,0]
	v_mov_b32_e32 v55, v53
	v_pk_add_f32 v[52:53], v[54:55], v[56:57]
	v_lshlrev_b32_e32 v54, 16, v86
	v_and_b32_e32 v55, 0xffff0000, v86
	v_lshlrev_b32_e32 v56, 16, v87
	v_and_b32_e32 v57, 0xffff0000, v87
	v_pk_mul_f32 v[54:55], v[48:49], v[54:55] op_sel_hi:[0,1]
	v_pk_mul_f32 v[56:57], v[48:49], v[56:57] op_sel_hi:[0,1]
	s_waitcnt vmcnt(9)
	v_pk_fma_f32 v[36:37], v[16:17], v[54:55], v[36:37]
	v_pk_fma_f32 v[38:39], v[18:19], v[56:57], v[38:39]
	v_mul_f32_e32 v50, v36, v36
	v_lshlrev_b32_e32 v60, 16, v85
	v_and_b32_e32 v61, 0xffff0000, v85
	v_pk_fma_f32 v[54:55], v[36:37], v[36:37], v[50:51] op_sel_hi:[1,1,0]
	v_mul_f32_e32 v50, v38, v38
	v_pk_mul_f32 v[58:59], v[48:49], v[58:59] op_sel_hi:[0,1]
	v_pk_mul_f32 v[48:49], v[48:49], v[60:61] op_sel_hi:[0,1]
	v_pk_add_f32 v[52:53], v[52:53], v[52:53] op_sel_hi:[0,1]
	v_pk_fma_f32 v[56:57], v[38:39], v[38:39], v[50:51] op_sel_hi:[1,1,0]
	s_waitcnt vmcnt(8)
	v_pk_fma_f32 v[34:35], v[26:27], v[48:49], v[34:35]
	v_pk_fma_f32 v[32:33], v[24:25], v[58:59], v[32:33]
	v_mul_f32_e32 v52, v34, v34
	v_mul_f32_e32 v54, v32, v32
	v_mul_f32_e32 v56, v33, v33
	v_mul_f32_e32 v50, v35, v35
	v_pk_add_f32 v[48:49], v[54:55], v[56:57]
	v_pk_add_f32 v[50:51], v[50:51], v[52:53]
	s_nop 0
	v_pk_add_f32 v[48:49], v[48:49], v[50:51]
	v_lshl_add_u64 v[50:51], v[76:77], 0, v[66:67]
	v_add_f32_e32 v48, v48, v49
	ds_bpermute_b32 v49, v92, v48
	s_waitcnt lgkmcnt(0)
	v_add_f32_e32 v48, v48, v49
	ds_bpermute_b32 v49, v93, v48
	s_waitcnt lgkmcnt(0)
	v_add_f32_e32 v48, v48, v49
	ds_bpermute_b32 v49, v94, v48
	s_waitcnt lgkmcnt(0)
	v_add_f32_e32 v52, v48, v49
	ds_bpermute_b32 v53, v95, v52
	v_cvt_pk_bf16_f32 v48, v44, v45
	v_cvt_pk_bf16_f32 v49, v46, v47
	global_store_dwordx2 v[50:51], v[48:49], off nt
	v_cvt_pk_bf16_f32 v48, v40, v41
	s_waitcnt lgkmcnt(0)
	v_add_f32_e32 v52, v52, v53
	ds_bpermute_b32 v53, v96, v52
	v_cvt_pk_bf16_f32 v49, v42, v43
	global_store_dwordx2 v[50:51], v[48:49], off offset:512 nt
	v_cvt_pk_bf16_f32 v48, v36, v37
	v_cvt_pk_bf16_f32 v49, v38, v39
	s_waitcnt lgkmcnt(0)
	v_add_f32_e32 v52, v52, v53
	ds_bpermute_b32 v53, v97, v52
	global_store_dwordx2 v[50:51], v[48:49], off offset:1024 nt
	v_cvt_pk_bf16_f32 v48, v32, v33
	s_waitcnt lgkmcnt(0)
	v_add_f32_e32 v49, v52, v53
	v_fmamk_f32 v49, v49, 0x3a800000, v65
	v_rsq_f32_e32 v52, v49
	v_cvt_pk_bf16_f32 v49, v34, v35
	global_store_dwordx2 v[50:51], v[48:49], off offset:1536 nt
	v_lshl_add_u64 v[48:49], v[82:83], 0, v[66:67]
	v_pk_mul_f32 v[44:45], v[44:45], v[52:53] op_sel_hi:[1,0]
	v_pk_mul_f32 v[46:47], v[46:47], v[52:53] op_sel_hi:[1,0]
	v_pk_mul_f32 v[44:45], v[4:5], v[44:45]
	v_pk_mul_f32 v[46:47], v[6:7], v[46:47]
	v_pk_mul_f32 v[40:41], v[40:41], v[52:53] op_sel_hi:[1,0]
	v_pk_mul_f32 v[42:43], v[42:43], v[52:53] op_sel_hi:[1,0]
	v_pk_mul_f32 v[36:37], v[36:37], v[52:53] op_sel_hi:[1,0]
	v_pk_mul_f32 v[38:39], v[38:39], v[52:53] op_sel_hi:[1,0]
	v_pk_mul_f32 v[32:33], v[32:33], v[52:53] op_sel_hi:[1,0]
	v_pk_mul_f32 v[34:35], v[34:35], v[52:53] op_sel_hi:[1,0]
	v_cvt_pk_bf16_f32 v44, v44, v45
	v_cvt_pk_bf16_f32 v45, v46, v47
	v_add_co_u32_e32 v46, vcc, s40, v48
	v_pk_mul_f32 v[42:43], v[14:15], v[42:43]
	v_pk_mul_f32 v[40:41], v[12:13], v[40:41]
	v_pk_mul_f32 v[38:39], v[22:23], v[38:39]
	v_pk_mul_f32 v[36:37], v[20:21], v[36:37]
	v_pk_mul_f32 v[34:35], v[30:31], v[34:35]
	v_pk_mul_f32 v[32:33], v[28:29], v[32:33]
	v_addc_co_u32_e32 v47, vcc, 0, v49, vcc
	v_cvt_pk_bf16_f32 v40, v40, v41
	v_cvt_pk_bf16_f32 v41, v42, v43
	v_cvt_pk_bf16_f32 v36, v36, v37
	v_cvt_pk_bf16_f32 v37, v38, v39
	v_cvt_pk_bf16_f32 v32, v32, v33
	v_cvt_pk_bf16_f32 v33, v34, v35
	global_store_dwordx2 v[46:47], v[44:45], off
	global_store_dwordx2 v[46:47], v[40:41], off offset:512
	global_store_dwordx2 v[46:47], v[36:37], off offset:1024
	global_store_dwordx2 v[46:47], v[32:33], off offset:1536
	s_branch .LBB0_952

; __device__ __forceinline__ float bf_lo(unsigned w) { return __uint_as_float(w << 16); }
; __device__ __forceinline__ float bf_hi(unsigned w) { return __uint_as_float(w & 0xffff0000u); }
; __device__ __forceinline__ void rows2_phase(const Params& p) {
;     ...
;     for (int r = gw; r < MR; r += 2 * NGW) {
;         u32x2 y[2][4], hb[2][4]; f32x4 qp[2][4];
; #pragma unroll
;         for (int q = 0; q < 2; ++q) { const size_t rr = (size_t)(r + q * NGW < MR ? r + q * NGW : r);
; #pragma unroll
;             for (int j = 0; j < 4; ++j) { y[q][j] = *((const u32x2*)(Y + rr * DM) + lane + 64 * j); hb[q][j] = *((const u32x2*)(p.out + rr * DM) + lane + 64 * j); qp[q][j] = part[rr * 4 + j]; } }
;         asm volatile("s_waitcnt vmcnt(0)" ::: "memory");
; #pragma unroll
;         for (int q = 0; q < 2; ++q) { const int rq = r + q * NGW; if (rq >= MR) break; const size_t rr = (size_t)rq;
;             const f32x4 qs = (qp[q][0] + qp[q][1]) + (qp[q][2] + qp[q][3]);
;             const float rs = __builtin_amdgcn_rsqf(((qs[0] + qs[1]) + (qs[2] + qs[3])) * (1.0f / DM) + EPS);
; #pragma unroll
;             for (int j = 0; j < 4; ++j) { const f32x4 yv = {bf_lo(y[q][j].x), bf_hi(y[q][j].x), bf_lo(y[q][j].y), bf_hi(y[q][j].y)};
;                 const f32x4 h1 = {bf_lo(hb[q][j].x), bf_hi(hb[q][j].x), bf_lo(hb[q][j].y), bf_hi(hb[q][j].y)};
;                 *(f32x4*)(p.out + rr * DM + 4 * lane + 256 * j) = h1 + yv * rs * gp[j]; } }
.LBB0_1182:
	v_ashrrev_i32_e32 v17, 31, v16
	s_waitcnt vmcnt(14)
	v_lshlrev_b64 v[20:21], 6, v[16:17]
	v_lshl_add_u64 v[20:21], s[10:11], 0, v[20:21]
	v_add_u32_e32 v38, s33, v16
	global_load_dwordx4 v[58:61], v[20:21], off
	global_load_dwordx4 v[62:65], v[20:21], off offset:16
	global_load_dwordx4 v[66:69], v[20:21], off offset:32
	global_load_dwordx4 v[70:73], v[20:21], off offset:48
	v_cmp_gt_i32_e32 vcc, s4, v38
	v_lshlrev_b64 v[18:19], 11, v[16:17]
	v_lshlrev_b64 v[76:77], 12, v[16:17]
	v_cndmask_b32_e32 v16, v16, v38, vcc
	v_lshl_add_u64 v[18:19], v[32:33], 0, v[18:19]
	v_lshl_add_u64 v[20:21], v[34:35], 0, v[76:77]
	v_ashrrev_i32_e32 v17, 31, v16
	global_load_dwordx2 v[74:75], v[18:19], off
	global_load_dwordx2 v[78:79], v[20:21], off
	global_load_dwordx2 v[80:81], v[18:19], off offset:512
	global_load_dwordx2 v[82:83], v[20:21], off offset:512
	global_load_dwordx2 v[84:85], v[18:19], off offset:1024
	global_load_dwordx2 v[86:87], v[20:21], off offset:1024
	global_load_dwordx2 v[88:89], v[18:19], off offset:1536
	global_load_dwordx2 v[90:91], v[20:21], off offset:1536
	v_lshlrev_b64 v[18:19], 11, v[16:17]
	v_lshlrev_b64 v[20:21], 12, v[16:17]
	v_lshlrev_b64 v[16:17], 6, v[16:17]
	v_lshl_add_u64 v[96:97], s[10:11], 0, v[16:17]
	v_lshl_add_u64 v[92:93], v[32:33], 0, v[18:19]
	v_lshl_add_u64 v[94:95], v[34:35], 0, v[20:21]
	global_load_dwordx4 v[16:19], v[96:97], off offset:48
	global_load_dwordx4 v[20:23], v[96:97], off offset:32
	global_load_dwordx4 v[24:27], v[96:97], off offset:16
	global_load_dwordx4 v[28:31], v[96:97], off
	global_load_dwordx2 v[52:53], v[92:93], off
	global_load_dwordx2 v[48:49], v[92:93], off offset:512
	global_load_dwordx2 v[44:45], v[92:93], off offset:1024
	global_load_dwordx2 v[40:41], v[92:93], off offset:1536
	global_load_dwordx2 v[54:55], v[94:95], off
	global_load_dwordx2 v[50:51], v[94:95], off offset:512
	global_load_dwordx2 v[46:47], v[94:95], off offset:1024
	global_load_dwordx2 v[42:43], v[94:95], off offset:1536
	v_lshl_add_u64 v[76:77], v[36:37], 0, v[76:77]
	s_waitcnt vmcnt(0)
	s_waitcnt vmcnt(22)
	v_pk_add_f32 v[60:61], v[60:61], v[64:65]
	v_pk_add_f32 v[58:59], v[58:59], v[62:63]
	s_waitcnt vmcnt(20)
	v_pk_add_f32 v[62:63], v[68:69], v[72:73]
	v_pk_add_f32 v[64:65], v[66:67], v[70:71]
	v_pk_add_f32 v[60:61], v[60:61], v[62:63]
	v_pk_add_f32 v[58:59], v[58:59], v[64:65]
	s_waitcnt vmcnt(18)
	v_lshlrev_b32_e32 v70, 16, v78
	v_pk_mov_b32 v[62:63], v[58:59], v[60:61] op_sel:[1,0]
	v_mov_b32_e32 v59, v61
	v_pk_add_f32 v[58:59], v[62:63], v[58:59]
	v_lshlrev_b32_e32 v66, 16, v74
	v_add_f32_e32 v39, v58, v59
	v_fmamk_f32 v39, v39, 0x3a800000, v56
	v_rsq_f32_e32 v96, v39
	v_and_b32_e32 v67, 0xffff0000, v74
	v_lshlrev_b32_e32 v68, 16, v75
	v_and_b32_e32 v69, 0xffff0000, v75
	v_and_b32_e32 v71, 0xffff0000, v78
	v_lshlrev_b32_e32 v72, 16, v79
	v_and_b32_e32 v73, 0xffff0000, v79
	s_waitcnt vmcnt(17)
	v_lshlrev_b32_e32 v74, 16, v80
	v_and_b32_e32 v75, 0xffff0000, v80
	v_lshlrev_b32_e32 v78, 16, v81
	v_and_b32_e32 v79, 0xffff0000, v81
	s_waitcnt vmcnt(15)
	v_lshlrev_b32_e32 v92, 16, v84
	v_and_b32_e32 v93, 0xffff0000, v84
	v_lshlrev_b32_e32 v84, 16, v85
	v_and_b32_e32 v85, 0xffff0000, v85
	v_pk_mul_f32 v[58:59], v[96:97], v[66:67] op_sel_hi:[0,1]
	v_pk_mul_f32 v[60:61], v[96:97], v[68:69] op_sel_hi:[0,1]
	v_lshlrev_b32_e32 v80, 16, v82
	v_and_b32_e32 v81, 0xffff0000, v82
	v_lshlrev_b32_e32 v82, 16, v83
	v_and_b32_e32 v83, 0xffff0000, v83
	s_waitcnt vmcnt(14)
	v_lshlrev_b32_e32 v94, 16, v86
	v_and_b32_e32 v95, 0xffff0000, v86
	v_lshlrev_b32_e32 v86, 16, v87
	v_and_b32_e32 v87, 0xffff0000, v87
	v_pk_mul_f32 v[62:63], v[96:97], v[74:75] op_sel_hi:[0,1]
	v_pk_mul_f32 v[64:65], v[96:97], v[78:79] op_sel_hi:[0,1]
	v_pk_mul_f32 v[66:67], v[96:97], v[92:93] op_sel_hi:[0,1]
	v_pk_mul_f32 v[68:69], v[96:97], v[84:85] op_sel_hi:[0,1]
	v_pk_fma_f32 v[60:61], v[2:3], v[60:61], v[72:73]
	v_pk_fma_f32 v[58:59], v[0:1], v[58:59], v[70:71]
	s_waitcnt vmcnt(13)
	v_lshlrev_b32_e32 v98, 16, v88
	v_and_b32_e32 v99, 0xffff0000, v88
	v_pk_fma_f32 v[64:65], v[6:7], v[64:65], v[82:83]
	v_pk_fma_f32 v[62:63], v[4:5], v[62:63], v[80:81]
	v_pk_fma_f32 v[68:69], v[10:11], v[68:69], v[86:87]
	v_pk_fma_f32 v[66:67], v[8:9], v[66:67], v[94:95]
	global_store_dwordx4 v[76:77], v[58:61], off nt
	global_store_dwordx4 v[76:77], v[62:65], off offset:1024 nt
	global_store_dwordx4 v[76:77], v[66:69], off offset:2048 nt
	v_lshlrev_b32_e32 v58, 16, v89
	v_and_b32_e32 v59, 0xffff0000, v89
	s_waitcnt vmcnt(15)
	v_lshlrev_b32_e32 v62, 16, v90
	v_and_b32_e32 v63, 0xffff0000, v90
	v_lshlrev_b32_e32 v60, 16, v91
	v_and_b32_e32 v61, 0xffff0000, v91
	v_pk_mul_f32 v[64:65], v[96:97], v[98:99] op_sel_hi:[0,1]
	v_pk_mul_f32 v[58:59], v[96:97], v[58:59] op_sel_hi:[0,1]
	v_pk_fma_f32 v[60:61], v[14:15], v[58:59], v[60:61]
	v_pk_fma_f32 v[58:59], v[12:13], v[64:65], v[62:63]
	global_store_dwordx4 v[76:77], v[58:61], off offset:3072 nt
	s_and_saveexec_b64 s[2:3], vcc
	s_cbranch_execz .LBB0_1181
; __device__ __forceinline__ float bf_lo(unsigned w) { return __uint_as_float(w << 16); }
; __device__ __forceinline__ float bf_hi(unsigned w) { return __uint_as_float(w & 0xffff0000u); }
; __device__ __forceinline__ void rows2_phase(const Params& p) {
;     ...
;         for (int q = 0; q < 2; ++q) { const int rq = r + q * NGW; if (rq >= MR) break; const size_t rr = (size_t)rq;
;             const f32x4 qs = (qp[q][0] + qp[q][1]) + (qp[q][2] + qp[q][3]);
;             const float rs = __builtin_amdgcn_rsqf(((qs[0] + qs[1]) + (qs[2] + qs[3])) * (1.0f / DM) + EPS);
; #pragma unroll
;             for (int j = 0; j < 4; ++j) { const f32x4 yv = {bf_lo(y[q][j].x), bf_hi(y[q][j].x), bf_lo(y[q][j].y), bf_hi(y[q][j].y)};
;                 const f32x4 h1 = {bf_lo(hb[q][j].x), bf_hi(hb[q][j].x), bf_lo(hb[q][j].y), bf_hi(hb[q][j].y)};
;                 *(f32x4*)(p.out + rr * DM + 4 * lane + 256 * j) = h1 + yv * rs * gp[j]; } }
	s_waitcnt vmcnt(12)
	v_pk_add_f32 v[26:27], v[30:31], v[26:27]
	v_pk_add_f32 v[24:25], v[28:29], v[24:25]
	v_pk_add_f32 v[16:17], v[20:21], v[16:17]
	v_pk_add_f32 v[18:19], v[22:23], v[18:19]
	v_pk_add_f32 v[16:17], v[24:25], v[16:17]
	v_pk_add_f32 v[18:19], v[26:27], v[18:19]
	v_ashrrev_i32_e32 v39, 31, v38
	v_pk_mov_b32 v[20:21], v[16:17], v[18:19] op_sel:[1,0]
	v_mov_b32_e32 v17, v19
	v_pk_add_f32 v[16:17], v[20:21], v[16:17]
	s_waitcnt vmcnt(11)
	v_lshlrev_b32_e32 v18, 16, v53
	v_add_f32_e32 v16, v16, v17
	v_fmamk_f32 v16, v16, 0x3a800000, v56
	v_rsq_f32_e32 v20, v16
	v_lshlrev_b32_e32 v16, 16, v52
	v_and_b32_e32 v17, 0xffff0000, v52
	v_and_b32_e32 v19, 0xffff0000, v53
	v_lshlrev_b64 v[22:23], 12, v[38:39]
	s_waitcnt vmcnt(7)
	v_lshlrev_b32_e32 v24, 16, v54
	v_and_b32_e32 v25, 0xffff0000, v54
	v_lshlrev_b32_e32 v26, 16, v55
	v_and_b32_e32 v27, 0xffff0000, v55
	v_pk_mul_f32 v[16:17], v[20:21], v[16:17] op_sel_hi:[0,1]
	v_pk_mul_f32 v[18:19], v[20:21], v[18:19] op_sel_hi:[0,1]
	v_pk_fma_f32 v[18:19], v[2:3], v[18:19], v[26:27]
	v_pk_fma_f32 v[16:17], v[0:1], v[16:17], v[24:25]
	v_lshl_add_u64 v[22:23], v[36:37], 0, v[22:23]
	global_store_dwordx4 v[22:23], v[16:19], off nt
	s_waitcnt vmcnt(7)
	v_lshlrev_b32_e32 v24, 16, v50
	v_and_b32_e32 v25, 0xffff0000, v50
	v_lshlrev_b32_e32 v16, 16, v48
	v_and_b32_e32 v17, 0xffff0000, v48
	v_lshlrev_b32_e32 v18, 16, v49
	v_and_b32_e32 v19, 0xffff0000, v49
	v_lshlrev_b32_e32 v26, 16, v51
	v_and_b32_e32 v27, 0xffff0000, v51
	v_pk_mul_f32 v[16:17], v[20:21], v[16:17] op_sel_hi:[0,1]
	v_pk_mul_f32 v[18:19], v[20:21], v[18:19] op_sel_hi:[0,1]
	v_pk_fma_f32 v[18:19], v[6:7], v[18:19], v[26:27]
	v_pk_fma_f32 v[16:17], v[4:5], v[16:17], v[24:25]
	global_store_dwordx4 v[22:23], v[16:19], off offset:1024 nt
	s_waitcnt vmcnt(7)
	v_lshlrev_b32_e32 v24, 16, v46
	v_and_b32_e32 v25, 0xffff0000, v46
	v_lshlrev_b32_e32 v16, 16, v44
	v_and_b32_e32 v17, 0xffff0000, v44
	v_lshlrev_b32_e32 v18, 16, v45
	v_and_b32_e32 v19, 0xffff0000, v45
	v_lshlrev_b32_e32 v26, 16, v47
	v_and_b32_e32 v27, 0xffff0000, v47
	v_pk_mul_f32 v[16:17], v[20:21], v[16:17] op_sel_hi:[0,1]
	v_pk_mul_f32 v[18:19], v[20:21], v[18:19] op_sel_hi:[0,1]
	v_pk_fma_f32 v[18:19], v[10:11], v[18:19], v[26:27]
	v_pk_fma_f32 v[16:17], v[8:9], v[16:17], v[24:25]
	global_store_dwordx4 v[22:23], v[16:19], off offset:2048 nt
	s_waitcnt vmcnt(7)
	v_lshlrev_b32_e32 v24, 16, v42
	v_and_b32_e32 v25, 0xffff0000, v42
	v_lshlrev_b32_e32 v16, 16, v40
	v_and_b32_e32 v17, 0xffff0000, v40
	v_lshlrev_b32_e32 v18, 16, v41
	v_and_b32_e32 v19, 0xffff0000, v41
	v_lshlrev_b32_e32 v26, 16, v43
	v_and_b32_e32 v27, 0xffff0000, v43
	v_pk_mul_f32 v[16:17], v[20:21], v[16:17] op_sel_hi:[0,1]
	v_pk_mul_f32 v[18:19], v[20:21], v[18:19] op_sel_hi:[0,1]
	v_pk_fma_f32 v[18:19], v[14:15], v[18:19], v[26:27]
	v_pk_fma_f32 v[16:17], v[12:13], v[16:17], v[24:25]
	global_store_dwordx4 v[22:23], v[16:19], off offset:3072 nt
	s_branch .LBB0_1181

; __global__ void __launch_bounds__(NTHREADS, 2) fwd_megakernel(Params p) {
	.amdhsa_kernel _Z14fwd_megakernel6Params
		.amdhsa_group_segment_fixed_size 0
		.amdhsa_private_segment_fixed_size 0
		.amdhsa_kernarg_size 424
		.amdhsa_user_sgpr_count 2
		.amdhsa_user_sgpr_dispatch_ptr 0
		.amdhsa_user_sgpr_queue_ptr 0
		.amdhsa_user_sgpr_kernarg_segment_ptr 1
		.amdhsa_user_sgpr_dispatch_id 0
		.amdhsa_user_sgpr_kernarg_preload_length 0
		.amdhsa_user_sgpr_kernarg_preload_offset 0
		.amdhsa_user_sgpr_private_segment_size 0
		.amdhsa_uses_dynamic_stack 0
		.amdhsa_enable_private_segment 0
		.amdhsa_system_sgpr_workgroup_id_x 1
		.amdhsa_system_sgpr_workgroup_id_y 0
		.amdhsa_system_sgpr_workgroup_id_z 0
		.amdhsa_system_sgpr_workgroup_info 0
		.amdhsa_system_vgpr_workitem_id 2
		.amdhsa_next_free_vgpr 254
		.amdhsa_next_free_sgpr 100
		.amdhsa_accum_offset 256
		.amdhsa_reserve_vcc 1
		.amdhsa_float_round_mode_32 0
		.amdhsa_float_round_mode_16_64 0
		.amdhsa_float_denorm_mode_32 3
		.amdhsa_float_denorm_mode_16_64 3
		.amdhsa_dx10_clamp 1
		.amdhsa_ieee_mode 1
		.amdhsa_fp16_overflow 0
		.amdhsa_tg_split 0
		.amdhsa_exception_fp_ieee_invalid_op 0
		.amdhsa_exception_fp_denorm_src 0
		.amdhsa_exception_fp_ieee_div_zero 0
		.amdhsa_exception_fp_ieee_overflow 0
		.amdhsa_exception_fp_ieee_underflow 0
		.amdhsa_exception_fp_ieee_inexact 0
		.amdhsa_exception_int_div_zero 0
	.end_amdhsa_kernel

; __global__ void __launch_bounds__(NTHREADS, 2) fwd_megakernel(Params p) {
.Lfunc_end0:
	.size	_Z14fwd_megakernel6Params, .Lfunc_end0-_Z14fwd_megakernel6Params
	.set _Z14fwd_megakernel6Params.num_vgpr, 254
	.set _Z14fwd_megakernel6Params.num_agpr, 0
	.set _Z14fwd_megakernel6Params.numbered_sgpr, 100
	.set _Z14fwd_megakernel6Params.num_named_barrier, 0
	.set _Z14fwd_megakernel6Params.private_seg_size, 0
	.set _Z14fwd_megakernel6Params.uses_vcc, 1
	.set _Z14fwd_megakernel6Params.uses_flat_scratch, 0
	.set _Z14fwd_megakernel6Params.has_dyn_sized_stack, 0
	.set _Z14fwd_megakernel6Params.has_recursion, 0
	.set _Z14fwd_megakernel6Params.has_indirect_call, 0

; __global__ void __launch_bounds__(NTHREADS, 2) fwd_megakernel(Params p) {
amdhsa.kernels:
  - .agpr_count:     0
    .args:
      - .offset:         0
        .size:           168
        .value_kind:     by_value
      - .offset:         168
        .size:           4
        .value_kind:     hidden_block_count_x
      - .offset:         172
        .size:           4
        .value_kind:     hidden_block_count_y
      - .offset:         176
        .size:           4
        .value_kind:     hidden_block_count_z
      - .offset:         180
        .size:           2
        .value_kind:     hidden_group_size_x
      - .offset:         182
        .size:           2
        .value_kind:     hidden_group_size_y
      - .offset:         184
        .size:           2
        .value_kind:     hidden_group_size_z
      - .offset:         186
        .size:           2
        .value_kind:     hidden_remainder_x
      - .offset:         188
        .size:           2
        .value_kind:     hidden_remainder_y
      - .offset:         190
        .size:           2
        .value_kind:     hidden_remainder_z
      - .offset:         208
        .size:           8
        .value_kind:     hidden_global_offset_x
      - .offset:         216
        .size:           8
        .value_kind:     hidden_global_offset_y
      - .offset:         224
        .size:           8
        .value_kind:     hidden_global_offset_z
      - .offset:         232
        .size:           2
        .value_kind:     hidden_grid_dims
      - .offset:         256
        .size:           8
        .value_kind:     hidden_multigrid_sync_arg
      - .offset:         288
        .size:           4
        .value_kind:     hidden_dynamic_lds_size
    .group_segment_fixed_size: 0
    .kernarg_segment_align: 8
    .kernarg_segment_size: 424
    .language:       OpenCL C
    .language_version:
      - 2
      - 0
    .max_flat_workgroup_size: 512
    .name:           _Z14fwd_megakernel6Params
    .private_segment_fixed_size: 0
    .sgpr_count:     106
    .sgpr_spill_count: 8
    .symbol:         _Z14fwd_megakernel6Params.kd
    .uniform_work_group_size: 1
    .uses_dynamic_stack: false
    .vgpr_count:     254
    .vgpr_spill_count: 0
    .wavefront_size: 64
